# K loops: pre-barrier vmcnt+lgkmcnt waits merged into one s_waitcnt, redundant post-barrier lgkmcnt(0) removed (on top of deleted setprio flips)
# baseline (speedup 1.0000x reference)
; #define PG8_STAGE(bufoff, gbase, voff) do { _Pragma("unroll") for (int _i = 0; _i < 2; ++_i) \
;         __builtin_amdgcn_global_load_lds((const unsigned*)((const char*)(gbase) + (voff)[_i]), (PG8_LAS unsigned*)(lds + (bufoff) + ldsw + _i * 8192), 16, 0, 0); } while (0)
; #define PG8_LDA(dst, b, h) do { _Pragma("unroll") for (int m = 0; m < 4; ++m) _Pragma("unroll") for (int k = 0; k < 2; ++k) dst[m][k] = *(const PG8_LAS bf16x8*)(lds + PG8_SA(b, h) + aoff + m * 2048 + k * 1024); } while (0)
; #define PG8_LDB(dst, b, h) do { _Pragma("unroll") for (int n = 0; n < 2; ++n) _Pragma("unroll") for (int k = 0; k < 2; ++k) dst[n][k] = *(const PG8_LAS bf16x8*)(lds + PG8_SB(b, h) + boff + n * 2048 + k * 1024); } while (0)
; #define PG8_MMA(ai, bj, At, Bt) do { __builtin_amdgcn_s_setprio(1); _Pragma("unroll") for (int m = 0; m < 4; ++m) _Pragma("unroll") for (int n = 0; n < 2; ++n) _Pragma("unroll") for (int k = 0; k < 2; ++k) \
;         acc[ai][bj][m][n] = __builtin_amdgcn_mfma_f32_16x16x32_bf16(Bt[n][k], At[m][k], acc[ai][bj][m][n], 0, 0, 0); __builtin_amdgcn_s_setprio(0); } while (0)
; #define PG8_WAIT_V(n) asm volatile("s_waitcnt vmcnt(" #n ")" ::: "memory")
; #define PG8_WAIT_L(n) asm volatile("s_waitcnt lgkmcnt(" #n ")" ::: "memory")
; template <class Epi, class Sched, bool ALIGN_EPI = false, bool SP2 = false>
; __device__ __forceinline__ void gemm_phase(PG8_LAS unsigned char* lds, const Gemm g, const Sched& S, const Epi& E) {
;     ...
;             const bool last = (t == nt - 2);
;             const char* a1 = cA + (size_t)(t + 1) * kstep;
;             const char* a2 = last ? nA : cA + (size_t)(t + 2) * kstep; const char* b2 = last ? nB : cB + (size_t)(t + 2) * kstep;
;             const char* a3 = a2 + kstep; const char* b3 = b2 + kstep;
;             if (last && has_next) S.a_ready(nxt);
;             if constexpr (SP2) {
;             PG8_LDB(B0, 0, 0); PG8_LDB(B1, 0, 1); PG8_SCHED; PG8_LDA(At, 0, 0); PG8_STAGE(PG8_SA(1, 1), a1 + hA, voffA);
;             PG8_WAIT_V(8); PG8_WAIT_L(0); PG8_BAR; PG8_MMA(0, 0, At, B0); PG8_MMA(0, 1, At, B1); PG8_BAR; PG8_SCHED;
;             PG8_LDA(At, 0, 1); PG8_STAGE(PG8_SB(0, 0), b2, voffB); PG8_STAGE(PG8_SB(0, 1), b2 + hB, voffB); PG8_STAGE(PG8_SA(0, 0), a2, voffA);
;             PG8_WAIT_V(8); PG8_WAIT_L(0); PG8_BAR; PG8_MMA(1, 0, At, B0); PG8_MMA(1, 1, At, B1); PG8_BAR; PG8_SCHED;
.LBB0_190:
	ds_read_b128 v[130:133], v229
	ds_read_b128 v[134:137], v229 offset:1024
	ds_read_b128 v[138:141], v229 offset:2048
	ds_read_b128 v[142:145], v229 offset:3072
	ds_read_b128 v[146:149], v230
	ds_read_b128 v[150:153], v230 offset:1024
	ds_read_b128 v[154:157], v230 offset:2048
	ds_read_b128 v[158:161], v230 offset:3072
	s_add_u32 s64, s62, 0xfff80080
	s_addc_u32 s65, s63, -1
	s_cmp_eq_u32 s97, 28
	s_cselect_b32 s67, s11, s65
	s_cselect_b32 s66, s33, s64
	s_cselect_b32 s65, s53, s96
	s_cselect_b32 s64, s55, s61
	v_lshl_add_u64 v[220:221], s[62:63], 0, v[212:213]
	s_add_i32 m0, s74, 0xc000
	ds_read_b128 v[162:165], v231
	ds_read_b128 v[166:169], v231 offset:1024
	ds_read_b128 v[170:173], v231 offset:2048
	ds_read_b128 v[174:177], v231 offset:3072
	ds_read_b128 v[178:181], v231 offset:4096
	ds_read_b128 v[182:185], v231 offset:5120
	ds_read_b128 v[186:189], v231 offset:6144
	ds_read_b128 v[190:193], v231 offset:7168
	global_load_lds_dwordx4 v[220:221], off
	v_lshl_add_u64 v[220:221], s[62:63], 0, v[214:215]
	s_add_i32 m0, s74, 0xe000
	s_nop 0
	global_load_lds_dwordx4 v[220:221], off
	s_waitcnt vmcnt(8) lgkmcnt(0)
	s_barrier
	v_mfma_f32_16x16x32_bf16 v[126:129], v[130:133], v[162:165], v[126:129]
	v_mfma_f32_16x16x32_bf16 v[122:125], v[138:141], v[162:165], v[122:125]
	v_mfma_f32_16x16x32_bf16 v[110:113], v[130:133], v[170:173], v[110:113]
	v_mfma_f32_16x16x32_bf16 v[106:109], v[138:141], v[170:173], v[106:109]
	v_mfma_f32_16x16x32_bf16 v[94:97], v[130:133], v[178:181], v[94:97]
	v_mfma_f32_16x16x32_bf16 v[90:93], v[138:141], v[178:181], v[90:93]
	v_mfma_f32_16x16x32_bf16 v[78:81], v[130:133], v[186:189], v[78:81]
	v_mfma_f32_16x16x32_bf16 v[74:77], v[138:141], v[186:189], v[74:77]
	v_mfma_f32_16x16x32_bf16 v[126:129], v[134:137], v[166:169], v[126:129]
	v_mfma_f32_16x16x32_bf16 v[122:125], v[142:145], v[166:169], v[122:125]
	v_mfma_f32_16x16x32_bf16 v[110:113], v[134:137], v[174:177], v[110:113]
	v_mfma_f32_16x16x32_bf16 v[106:109], v[142:145], v[174:177], v[106:109]
	v_mfma_f32_16x16x32_bf16 v[94:97], v[134:137], v[182:185], v[94:97]
	v_mfma_f32_16x16x32_bf16 v[90:93], v[142:145], v[182:185], v[90:93]
	v_mfma_f32_16x16x32_bf16 v[78:81], v[134:137], v[190:193], v[78:81]
	v_mfma_f32_16x16x32_bf16 v[74:77], v[142:145], v[190:193], v[74:77]
	v_mfma_f32_16x16x32_bf16 v[118:121], v[146:149], v[162:165], v[118:121]
	v_mfma_f32_16x16x32_bf16 v[114:117], v[154:157], v[162:165], v[114:117]
	v_mfma_f32_16x16x32_bf16 v[102:105], v[146:149], v[170:173], v[102:105]
	v_mfma_f32_16x16x32_bf16 v[98:101], v[154:157], v[170:173], v[98:101]
	v_mfma_f32_16x16x32_bf16 v[86:89], v[146:149], v[178:181], v[86:89]
	v_mfma_f32_16x16x32_bf16 v[82:85], v[154:157], v[178:181], v[82:85]
	v_mfma_f32_16x16x32_bf16 v[70:73], v[146:149], v[186:189], v[70:73]
	v_mfma_f32_16x16x32_bf16 v[66:69], v[154:157], v[186:189], v[66:69]
	v_mfma_f32_16x16x32_bf16 v[118:121], v[150:153], v[166:169], v[118:121]
	v_mfma_f32_16x16x32_bf16 v[114:117], v[158:161], v[166:169], v[114:117]
	v_mfma_f32_16x16x32_bf16 v[102:105], v[150:153], v[174:177], v[102:105]
	v_mfma_f32_16x16x32_bf16 v[98:101], v[158:161], v[174:177], v[98:101]
	v_mfma_f32_16x16x32_bf16 v[86:89], v[150:153], v[182:185], v[86:89]
	v_mfma_f32_16x16x32_bf16 v[82:85], v[158:161], v[182:185], v[82:85]
	v_mfma_f32_16x16x32_bf16 v[70:73], v[150:153], v[190:193], v[70:73]
	v_mfma_f32_16x16x32_bf16 v[66:69], v[158:161], v[190:193], v[66:69]
	s_barrier
	s_add_i32 vcc_lo, s84, s73
	v_lshl_add_u64 v[220:221], s[64:65], 0, v[196:197]
	s_mov_b32 m0, vcc_lo
	ds_read_b128 v[162:165], v231 offset:16384
	ds_read_b128 v[166:169], v231 offset:17408
	ds_read_b128 v[170:173], v231 offset:18432
	ds_read_b128 v[174:177], v231 offset:19456
	ds_read_b128 v[178:181], v231 offset:20480
	ds_read_b128 v[182:185], v231 offset:21504
	ds_read_b128 v[186:189], v231 offset:22528
	ds_read_b128 v[190:193], v231 offset:23552
	global_load_lds_dwordx4 v[220:221], off
	s_add_i32 m0, vcc_lo, 0x2000
	s_add_u32 vcc_lo, s64, 0x80000
	v_lshl_add_u64 v[236:237], s[64:65], 0, v[200:201]
	s_addc_u32 vcc_hi, s65, 0
	s_add_i32 s86, s85, s73
	global_load_lds_dwordx4 v[236:237], off
	v_lshl_add_u64 v[238:239], vcc, 0, v[196:197]
	s_mov_b32 m0, s86
	v_lshl_add_u64 v[240:241], s[66:67], 0, v[198:199]
	global_load_lds_dwordx4 v[238:239], off
	v_lshl_add_u64 v[238:239], vcc, 0, v[200:201]
	s_add_i32 m0, s86, 0x2000
	s_nop 0
	global_load_lds_dwordx4 v[238:239], off
	v_lshl_add_u64 v[238:239], s[66:67], 0, v[194:195]
	s_mov_b32 m0, s74
	s_nop 0
	global_load_lds_dwordx4 v[238:239], off
	s_mov_b32 m0, s75
	s_nop 0
	global_load_lds_dwordx4 v[240:241], off
	s_waitcnt vmcnt(8) lgkmcnt(0)
	s_barrier
; #define PG8_STAGE(bufoff, gbase, voff) do { _Pragma("unroll") for (int _i = 0; _i < 2; ++_i) \
;         __builtin_amdgcn_global_load_lds((const unsigned*)((const char*)(gbase) + (voff)[_i]), (PG8_LAS unsigned*)(lds + (bufoff) + ldsw + _i * 8192), 16, 0, 0); } while (0)
; #define PG8_LDA(dst, b, h) do { _Pragma("unroll") for (int m = 0; m < 4; ++m) _Pragma("unroll") for (int k = 0; k < 2; ++k) dst[m][k] = *(const PG8_LAS bf16x8*)(lds + PG8_SA(b, h) + aoff + m * 2048 + k * 1024); } while (0)
; #define PG8_LDB(dst, b, h) do { _Pragma("unroll") for (int n = 0; n < 2; ++n) _Pragma("unroll") for (int k = 0; k < 2; ++k) dst[n][k] = *(const PG8_LAS bf16x8*)(lds + PG8_SB(b, h) + boff + n * 2048 + k * 1024); } while (0)
; #define PG8_MMA(ai, bj, At, Bt) do { __builtin_amdgcn_s_setprio(1); _Pragma("unroll") for (int m = 0; m < 4; ++m) _Pragma("unroll") for (int n = 0; n < 2; ++n) _Pragma("unroll") for (int k = 0; k < 2; ++k) \
;         acc[ai][bj][m][n] = __builtin_amdgcn_mfma_f32_16x16x32_bf16(Bt[n][k], At[m][k], acc[ai][bj][m][n], 0, 0, 0); __builtin_amdgcn_s_setprio(0); } while (0)
; #define PG8_WAIT_V(n) asm volatile("s_waitcnt vmcnt(" #n ")" ::: "memory")
; #define PG8_WAIT_L(n) asm volatile("s_waitcnt lgkmcnt(" #n ")" ::: "memory")
; #define PG8_BAR __builtin_amdgcn_s_barrier()
; #define PG8_SCHED __builtin_amdgcn_sched_barrier(0)
; template <class Epi, class Sched, bool ALIGN_EPI = false, bool SP2 = false>
; __device__ __forceinline__ void gemm_phase(PG8_LAS unsigned char* lds, const Gemm g, const Sched& S, const Epi& E) {
;     ...
;             PG8_WAIT_V(8); PG8_WAIT_L(0); PG8_BAR; PG8_MMA(1, 0, At, B0); PG8_MMA(1, 1, At, B1); PG8_BAR; PG8_SCHED;
;             PG8_LDB(B0, 1, 0); PG8_LDB(B1, 1, 1); PG8_SCHED; PG8_LDA(At, 1, 0); PG8_STAGE(PG8_SA(0, 1), a2 + hA, voffA);
;             PG8_WAIT_V(8); PG8_WAIT_L(0); PG8_BAR; PG8_MMA(0, 0, At, B0); PG8_MMA(0, 1, At, B1); PG8_BAR; PG8_SCHED;
	v_mfma_f32_16x16x32_bf16 v[62:65], v[130:133], v[162:165], v[62:65]
	v_mfma_f32_16x16x32_bf16 v[58:61], v[138:141], v[162:165], v[58:61]
	v_mfma_f32_16x16x32_bf16 v[46:49], v[130:133], v[170:173], v[46:49]
	v_mfma_f32_16x16x32_bf16 v[42:45], v[138:141], v[170:173], v[42:45]
	v_mfma_f32_16x16x32_bf16 v[30:33], v[130:133], v[178:181], v[30:33]
	v_mfma_f32_16x16x32_bf16 v[26:29], v[138:141], v[178:181], v[26:29]
	v_mfma_f32_16x16x32_bf16 v[14:17], v[130:133], v[186:189], v[14:17]
	v_mfma_f32_16x16x32_bf16 v[10:13], v[138:141], v[186:189], v[10:13]
	v_mfma_f32_16x16x32_bf16 v[62:65], v[134:137], v[166:169], v[62:65]
	v_mfma_f32_16x16x32_bf16 v[58:61], v[142:145], v[166:169], v[58:61]
	v_mfma_f32_16x16x32_bf16 v[46:49], v[134:137], v[174:177], v[46:49]
	v_mfma_f32_16x16x32_bf16 v[42:45], v[142:145], v[174:177], v[42:45]
	v_mfma_f32_16x16x32_bf16 v[30:33], v[134:137], v[182:185], v[30:33]
	v_mfma_f32_16x16x32_bf16 v[26:29], v[142:145], v[182:185], v[26:29]
	v_mfma_f32_16x16x32_bf16 v[14:17], v[134:137], v[190:193], v[14:17]
	v_mfma_f32_16x16x32_bf16 v[10:13], v[142:145], v[190:193], v[10:13]
	v_mfma_f32_16x16x32_bf16 v[54:57], v[146:149], v[162:165], v[54:57]
	v_mfma_f32_16x16x32_bf16 v[50:53], v[154:157], v[162:165], v[50:53]
	v_mfma_f32_16x16x32_bf16 v[38:41], v[146:149], v[170:173], v[38:41]
	v_mfma_f32_16x16x32_bf16 v[34:37], v[154:157], v[170:173], v[34:37]
	v_mfma_f32_16x16x32_bf16 v[22:25], v[146:149], v[178:181], v[22:25]
	v_mfma_f32_16x16x32_bf16 v[18:21], v[154:157], v[178:181], v[18:21]
	v_mfma_f32_16x16x32_bf16 v[6:9], v[146:149], v[186:189], v[6:9]
	v_mfma_f32_16x16x32_bf16 v[2:5], v[154:157], v[186:189], v[2:5]
	v_mfma_f32_16x16x32_bf16 v[54:57], v[150:153], v[166:169], v[54:57]
	v_mfma_f32_16x16x32_bf16 v[50:53], v[158:161], v[166:169], v[50:53]
	v_mfma_f32_16x16x32_bf16 v[38:41], v[150:153], v[174:177], v[38:41]
	v_mfma_f32_16x16x32_bf16 v[34:37], v[158:161], v[174:177], v[34:37]
	v_mfma_f32_16x16x32_bf16 v[22:25], v[150:153], v[182:185], v[22:25]
	v_mfma_f32_16x16x32_bf16 v[18:21], v[158:161], v[182:185], v[18:21]
	v_mfma_f32_16x16x32_bf16 v[6:9], v[150:153], v[190:193], v[6:9]
	v_mfma_f32_16x16x32_bf16 v[2:5], v[158:161], v[190:193], v[2:5]
	s_barrier
	s_add_i32 s86, 0, 0x18000
	s_add_i32 vcc_lo, 0, 0x1c000
	v_add_u32_e32 v142, s86, v223
	v_add_u32_e32 v158, vcc_lo, v223
	ds_read_b128 v[130:133], v142
	ds_read_b128 v[134:137], v142 offset:1024
	ds_read_b128 v[138:141], v142 offset:2048
	ds_read_b128 v[142:145], v142 offset:3072
	ds_read_b128 v[146:149], v158
	ds_read_b128 v[150:153], v158 offset:1024
	ds_read_b128 v[154:157], v158 offset:2048
	ds_read_b128 v[158:161], v158 offset:3072
	s_add_u32 s66, s66, 0x80000
	s_addc_u32 s67, s67, 0
	s_mov_b32 m0, s76
	v_lshl_add_u64 v[242:243], s[66:67], 0, v[194:195]
	ds_read_b128 v[162:165], v231 offset:32768
	ds_read_b128 v[166:169], v231 offset:33792
	ds_read_b128 v[170:173], v231 offset:34816
	ds_read_b128 v[174:177], v231 offset:35840
	ds_read_b128 v[178:181], v231 offset:36864
	ds_read_b128 v[182:185], v231 offset:37888
	ds_read_b128 v[186:189], v231 offset:38912
	ds_read_b128 v[190:193], v231 offset:39936
	global_load_lds_dwordx4 v[242:243], off
	v_lshl_add_u64 v[242:243], s[66:67], 0, v[198:199]
	s_mov_b32 m0, s77
	s_nop 0
	global_load_lds_dwordx4 v[242:243], off
	s_waitcnt vmcnt(8) lgkmcnt(0)
	s_barrier
	v_mfma_f32_16x16x32_bf16 v[126:129], v[130:133], v[162:165], v[126:129]
	v_mfma_f32_16x16x32_bf16 v[122:125], v[138:141], v[162:165], v[122:125]
	v_mfma_f32_16x16x32_bf16 v[110:113], v[130:133], v[170:173], v[110:113]
	v_mfma_f32_16x16x32_bf16 v[106:109], v[138:141], v[170:173], v[106:109]
	v_mfma_f32_16x16x32_bf16 v[94:97], v[130:133], v[178:181], v[94:97]
	v_mfma_f32_16x16x32_bf16 v[90:93], v[138:141], v[178:181], v[90:93]
	v_mfma_f32_16x16x32_bf16 v[78:81], v[130:133], v[186:189], v[78:81]
	v_mfma_f32_16x16x32_bf16 v[74:77], v[138:141], v[186:189], v[74:77]
	v_mfma_f32_16x16x32_bf16 v[126:129], v[134:137], v[166:169], v[126:129]
	v_mfma_f32_16x16x32_bf16 v[122:125], v[142:145], v[166:169], v[122:125]
	v_mfma_f32_16x16x32_bf16 v[110:113], v[134:137], v[174:177], v[110:113]
	v_mfma_f32_16x16x32_bf16 v[106:109], v[142:145], v[174:177], v[106:109]
	v_mfma_f32_16x16x32_bf16 v[94:97], v[134:137], v[182:185], v[94:97]
	v_mfma_f32_16x16x32_bf16 v[90:93], v[142:145], v[182:185], v[90:93]
	v_mfma_f32_16x16x32_bf16 v[78:81], v[134:137], v[190:193], v[78:81]
	v_mfma_f32_16x16x32_bf16 v[74:77], v[142:145], v[190:193], v[74:77]
	v_mfma_f32_16x16x32_bf16 v[118:121], v[146:149], v[162:165], v[118:121]
	v_mfma_f32_16x16x32_bf16 v[114:117], v[154:157], v[162:165], v[114:117]
	v_mfma_f32_16x16x32_bf16 v[102:105], v[146:149], v[170:173], v[102:105]
	v_mfma_f32_16x16x32_bf16 v[98:101], v[154:157], v[170:173], v[98:101]
	v_mfma_f32_16x16x32_bf16 v[86:89], v[146:149], v[178:181], v[86:89]
	v_mfma_f32_16x16x32_bf16 v[82:85], v[154:157], v[178:181], v[82:85]
	v_mfma_f32_16x16x32_bf16 v[70:73], v[146:149], v[186:189], v[70:73]
	v_mfma_f32_16x16x32_bf16 v[66:69], v[154:157], v[186:189], v[66:69]
	v_mfma_f32_16x16x32_bf16 v[118:121], v[150:153], v[166:169], v[118:121]
	v_mfma_f32_16x16x32_bf16 v[114:117], v[158:161], v[166:169], v[114:117]
	v_mfma_f32_16x16x32_bf16 v[102:105], v[150:153], v[174:177], v[102:105]
	v_mfma_f32_16x16x32_bf16 v[98:101], v[158:161], v[174:177], v[98:101]
	v_mfma_f32_16x16x32_bf16 v[86:89], v[150:153], v[182:185], v[86:89]
	v_mfma_f32_16x16x32_bf16 v[82:85], v[158:161], v[182:185], v[82:85]
	v_mfma_f32_16x16x32_bf16 v[70:73], v[150:153], v[190:193], v[70:73]
	v_mfma_f32_16x16x32_bf16 v[66:69], v[158:161], v[190:193], v[66:69]
	s_barrier
; #define PG8_STAGE(bufoff, gbase, voff) do { _Pragma("unroll") for (int _i = 0; _i < 2; ++_i) \
;         __builtin_amdgcn_global_load_lds((const unsigned*)((const char*)(gbase) + (voff)[_i]), (PG8_LAS unsigned*)(lds + (bufoff) + ldsw + _i * 8192), 16, 0, 0); } while (0)
; #define PG8_LDA(dst, b, h) do { _Pragma("unroll") for (int m = 0; m < 4; ++m) _Pragma("unroll") for (int k = 0; k < 2; ++k) dst[m][k] = *(const PG8_LAS bf16x8*)(lds + PG8_SA(b, h) + aoff + m * 2048 + k * 1024); } while (0)
; #define PG8_MMA(ai, bj, At, Bt) do { __builtin_amdgcn_s_setprio(1); _Pragma("unroll") for (int m = 0; m < 4; ++m) _Pragma("unroll") for (int n = 0; n < 2; ++n) _Pragma("unroll") for (int k = 0; k < 2; ++k) \
;         acc[ai][bj][m][n] = __builtin_amdgcn_mfma_f32_16x16x32_bf16(Bt[n][k], At[m][k], acc[ai][bj][m][n], 0, 0, 0); __builtin_amdgcn_s_setprio(0); } while (0)
; #define PG8_WAIT_V(n) asm volatile("s_waitcnt vmcnt(" #n ")" ::: "memory")
; #define PG8_WAIT_L(n) asm volatile("s_waitcnt lgkmcnt(" #n ")" ::: "memory")
; #define PG8_BAR __builtin_amdgcn_s_barrier()
; #define PG8_SCHED __builtin_amdgcn_sched_barrier(0)
; template <class Epi, class Sched, bool ALIGN_EPI = false, bool SP2 = false>
; __device__ __forceinline__ void gemm_phase(PG8_LAS unsigned char* lds, const Gemm g, const Sched& S, const Epi& E) {
;     ...
;             PG8_LDA(At, 1, 1); PG8_STAGE(PG8_SB(1, 0), b3, voffB); PG8_STAGE(PG8_SB(1, 1), b3 + hB, voffB); PG8_STAGE(PG8_SA(1, 0), a3, voffA);
;             PG8_WAIT_V(8); PG8_WAIT_L(0); PG8_BAR; PG8_MMA(1, 0, At, B0); PG8_MMA(1, 1, At, B1); PG8_BAR; PG8_SCHED;
;     __device__ __forceinline__ void operator()(AccRef acc, const pg8::Unit& u, int wr, int wc, int fr, int fq) const {
;         const int pn = u.pn, row0 = u.pm * 256 + wr * 64 + fr, cl = wc * 32 + 8 * fq;
;         if (pn < 16) {
	s_add_i32 s66, s86, s73
	v_lshl_add_u64 v[220:221], v[220:221], 0, s[38:39]
	s_mov_b32 m0, s66
	ds_read_b128 v[162:165], v231 offset:49152
	ds_read_b128 v[166:169], v231 offset:50176
	ds_read_b128 v[170:173], v231 offset:51200
	ds_read_b128 v[174:177], v231 offset:52224
	ds_read_b128 v[178:181], v231 offset:53248
	ds_read_b128 v[182:185], v231 offset:54272
	ds_read_b128 v[186:189], v231 offset:55296
	ds_read_b128 v[190:193], v231 offset:56320
	global_load_lds_dwordx4 v[220:221], off
	s_add_i32 m0, s66, 0x2000
	s_add_u32 s64, s64, 0x80080
	v_lshl_add_u64 v[220:221], v[236:237], 0, s[38:39]
	s_addc_u32 s65, s65, 0
	s_add_i32 s66, vcc_lo, s73
	global_load_lds_dwordx4 v[220:221], off
	v_lshl_add_u64 v[220:221], s[64:65], 0, v[196:197]
	s_mov_b32 m0, s66
	s_nop 0
	global_load_lds_dwordx4 v[220:221], off
	v_lshl_add_u64 v[220:221], s[64:65], 0, v[200:201]
	s_add_i32 m0, s66, 0x2000
	s_nop 0
	global_load_lds_dwordx4 v[220:221], off
	v_lshl_add_u64 v[220:221], v[238:239], 0, s[38:39]
	s_mov_b32 m0, s81
	s_nop 0
	global_load_lds_dwordx4 v[220:221], off
	v_lshl_add_u64 v[220:221], v[240:241], 0, s[38:39]
	s_mov_b32 m0, s82
	s_nop 0
	global_load_lds_dwordx4 v[220:221], off
	s_waitcnt vmcnt(8) lgkmcnt(0)
	s_barrier
	v_mfma_f32_16x16x32_bf16 v[62:65], v[130:133], v[162:165], v[62:65]
	v_mfma_f32_16x16x32_bf16 v[58:61], v[138:141], v[162:165], v[58:61]
	v_mfma_f32_16x16x32_bf16 v[46:49], v[130:133], v[170:173], v[46:49]
	v_mfma_f32_16x16x32_bf16 v[42:45], v[138:141], v[170:173], v[42:45]
	v_mfma_f32_16x16x32_bf16 v[30:33], v[130:133], v[178:181], v[30:33]
	v_mfma_f32_16x16x32_bf16 v[26:29], v[138:141], v[178:181], v[26:29]
	v_mfma_f32_16x16x32_bf16 v[14:17], v[130:133], v[186:189], v[14:17]
	v_mfma_f32_16x16x32_bf16 v[10:13], v[138:141], v[186:189], v[10:13]
	v_mfma_f32_16x16x32_bf16 v[62:65], v[134:137], v[166:169], v[62:65]
	v_mfma_f32_16x16x32_bf16 v[58:61], v[142:145], v[166:169], v[58:61]
	v_mfma_f32_16x16x32_bf16 v[46:49], v[134:137], v[174:177], v[46:49]
	v_mfma_f32_16x16x32_bf16 v[42:45], v[142:145], v[174:177], v[42:45]
	v_mfma_f32_16x16x32_bf16 v[30:33], v[134:137], v[182:185], v[30:33]
	v_mfma_f32_16x16x32_bf16 v[26:29], v[142:145], v[182:185], v[26:29]
	v_mfma_f32_16x16x32_bf16 v[14:17], v[134:137], v[190:193], v[14:17]
	v_mfma_f32_16x16x32_bf16 v[10:13], v[142:145], v[190:193], v[10:13]
	v_mfma_f32_16x16x32_bf16 v[54:57], v[146:149], v[162:165], v[54:57]
	v_mfma_f32_16x16x32_bf16 v[50:53], v[154:157], v[162:165], v[50:53]
	v_mfma_f32_16x16x32_bf16 v[38:41], v[146:149], v[170:173], v[38:41]
	v_mfma_f32_16x16x32_bf16 v[34:37], v[154:157], v[170:173], v[34:37]
	v_mfma_f32_16x16x32_bf16 v[22:25], v[146:149], v[178:181], v[22:25]
	v_mfma_f32_16x16x32_bf16 v[18:21], v[154:157], v[178:181], v[18:21]
	v_mfma_f32_16x16x32_bf16 v[6:9], v[146:149], v[186:189], v[6:9]
	v_mfma_f32_16x16x32_bf16 v[2:5], v[154:157], v[186:189], v[2:5]
	v_mfma_f32_16x16x32_bf16 v[54:57], v[150:153], v[166:169], v[54:57]
	v_mfma_f32_16x16x32_bf16 v[50:53], v[158:161], v[166:169], v[50:53]
	v_mfma_f32_16x16x32_bf16 v[38:41], v[150:153], v[174:177], v[38:41]
	v_mfma_f32_16x16x32_bf16 v[34:37], v[158:161], v[174:177], v[34:37]
	v_mfma_f32_16x16x32_bf16 v[22:25], v[150:153], v[182:185], v[22:25]
	v_mfma_f32_16x16x32_bf16 v[18:21], v[158:161], v[182:185], v[18:21]
	v_mfma_f32_16x16x32_bf16 v[6:9], v[150:153], v[190:193], v[6:9]
	v_mfma_f32_16x16x32_bf16 v[2:5], v[158:161], v[190:193], v[2:5]
	s_barrier
	s_add_i32 s97, s97, 2
	s_add_u32 s62, s62, 0x100
	s_addc_u32 s63, s63, 0
	s_add_u32 s61, s61, 0x100
	s_addc_u32 s96, s96, 0
	s_cmp_gt_u32 s97, 29
	s_cbranch_scc0 .LBB0_190
	s_and_b64 vcc, exec, s[40:41]
	s_cbranch_vccz .LBB0_211
	s_barrier
	v_lshl_add_u32 v220, s60, 8, v1
	s_cmp_gt_i32 s10, 15
	s_mov_b64 s[60:61], -1
	s_cbranch_scc1 .LBB0_212

; #define PG8_STAGE(bufoff, gbase, voff) do { _Pragma("unroll") for (int _i = 0; _i < 2; ++_i) \
;         __builtin_amdgcn_global_load_lds((const unsigned*)((const char*)(gbase) + (voff)[_i]), (PG8_LAS unsigned*)(lds + (bufoff) + ldsw + _i * 8192), 16, 0, 0); } while (0)
; #define PG8_LDA(dst, b, h) do { _Pragma("unroll") for (int m = 0; m < 4; ++m) _Pragma("unroll") for (int k = 0; k < 2; ++k) dst[m][k] = *(const PG8_LAS bf16x8*)(lds + PG8_SA(b, h) + aoff + m * 2048 + k * 1024); } while (0)
; #define PG8_LDB(dst, b, h) do { _Pragma("unroll") for (int n = 0; n < 2; ++n) _Pragma("unroll") for (int k = 0; k < 2; ++k) dst[n][k] = *(const PG8_LAS bf16x8*)(lds + PG8_SB(b, h) + boff + n * 2048 + k * 1024); } while (0)
; #define PG8_MMA(ai, bj, At, Bt) do { __builtin_amdgcn_s_setprio(1); _Pragma("unroll") for (int m = 0; m < 4; ++m) _Pragma("unroll") for (int n = 0; n < 2; ++n) _Pragma("unroll") for (int k = 0; k < 2; ++k) \
;         acc[ai][bj][m][n] = __builtin_amdgcn_mfma_f32_16x16x32_bf16(Bt[n][k], At[m][k], acc[ai][bj][m][n], 0, 0, 0); __builtin_amdgcn_s_setprio(0); } while (0)
; #define PG8_WAIT_V(n) asm volatile("s_waitcnt vmcnt(" #n ")" ::: "memory")
; #define PG8_WAIT_L(n) asm volatile("s_waitcnt lgkmcnt(" #n ")" ::: "memory")
; template <class Epi, class Sched, bool ALIGN_EPI = false, bool SP2 = false>
; __device__ __forceinline__ void gemm_phase(PG8_LAS unsigned char* lds, const Gemm g, const Sched& S, const Epi& E) {
;     ...
;             const bool last = (t == nt - 2);
;             const char* a1 = cA + (size_t)(t + 1) * kstep;
;             const char* a2 = last ? nA : cA + (size_t)(t + 2) * kstep; const char* b2 = last ? nB : cB + (size_t)(t + 2) * kstep;
;             const char* a3 = a2 + kstep; const char* b3 = b2 + kstep;
;             if (last && has_next) S.a_ready(nxt);
;             if constexpr (SP2) {
;             PG8_LDB(B0, 0, 0); PG8_LDB(B1, 0, 1); PG8_SCHED; PG8_LDA(At, 0, 0); PG8_STAGE(PG8_SA(1, 1), a1 + hA, voffA);
;             PG8_WAIT_V(8); PG8_WAIT_L(0); PG8_BAR; PG8_MMA(0, 0, At, B0); PG8_MMA(0, 1, At, B1); PG8_BAR; PG8_SCHED;
;             PG8_LDA(At, 0, 1); PG8_STAGE(PG8_SB(0, 0), b2, voffB); PG8_STAGE(PG8_SB(0, 1), b2 + hB, voffB); PG8_STAGE(PG8_SA(0, 0), a2, voffA);
;             PG8_WAIT_V(8); PG8_WAIT_L(0); PG8_BAR; PG8_MMA(1, 0, At, B0); PG8_MMA(1, 1, At, B1); PG8_BAR; PG8_SCHED;
.LBB0_868:
	ds_read_b128 v[146:149], v156
	ds_read_b128 v[150:153], v156 offset:1024
	ds_read_b128 v[160:163], v156 offset:2048
	ds_read_b128 v[164:167], v156 offset:3072
	ds_read_b128 v[168:171], v157
	ds_read_b128 v[172:175], v157 offset:1024
	ds_read_b128 v[176:179], v157 offset:2048
	ds_read_b128 v[180:183], v157 offset:3072
	s_add_u32 s18, s42, 0xfffc0080
	s_addc_u32 s19, s43, -1
	s_cmp_eq_u32 s72, 12
	s_cselect_b32 s47, s23, s19
	s_cselect_b32 s46, s67, s18
	s_cselect_b32 s45, s21, s71
	s_cselect_b32 s44, s69, s70
	v_lshl_add_u64 v[216:217], s[42:43], 0, v[138:139]
	s_add_i32 m0, s41, 0xc000
	ds_read_b128 v[184:187], v158
	ds_read_b128 v[188:191], v158 offset:1024
	ds_read_b128 v[192:195], v158 offset:2048
	ds_read_b128 v[196:199], v158 offset:3072
	ds_read_b128 v[200:203], v158 offset:4096
	ds_read_b128 v[204:207], v158 offset:5120
	ds_read_b128 v[208:211], v158 offset:6144
	ds_read_b128 v[212:215], v158 offset:7168
	global_load_lds_dwordx4 v[216:217], off
	v_lshl_add_u64 v[216:217], s[42:43], 0, v[140:141]
	s_add_i32 m0, s41, 0xe000
	s_nop 0
	global_load_lds_dwordx4 v[216:217], off
	s_waitcnt vmcnt(8) lgkmcnt(0)
	s_barrier
	v_mfma_f32_16x16x32_bf16 v[126:129], v[146:149], v[184:187], v[126:129]
	v_mfma_f32_16x16x32_bf16 v[122:125], v[160:163], v[184:187], v[122:125]
	v_mfma_f32_16x16x32_bf16 v[114:117], v[146:149], v[192:195], v[114:117]
	v_mfma_f32_16x16x32_bf16 v[106:109], v[160:163], v[192:195], v[106:109]
	v_mfma_f32_16x16x32_bf16 v[98:101], v[146:149], v[200:203], v[98:101]
	v_mfma_f32_16x16x32_bf16 v[90:93], v[160:163], v[200:203], v[90:93]
	v_mfma_f32_16x16x32_bf16 v[82:85], v[146:149], v[208:211], v[82:85]
	v_mfma_f32_16x16x32_bf16 v[74:77], v[160:163], v[208:211], v[74:77]
	v_mfma_f32_16x16x32_bf16 v[126:129], v[150:153], v[188:191], v[126:129]
	v_mfma_f32_16x16x32_bf16 v[122:125], v[164:167], v[188:191], v[122:125]
	v_mfma_f32_16x16x32_bf16 v[114:117], v[150:153], v[196:199], v[114:117]
	v_mfma_f32_16x16x32_bf16 v[106:109], v[164:167], v[196:199], v[106:109]
	v_mfma_f32_16x16x32_bf16 v[98:101], v[150:153], v[204:207], v[98:101]
	v_mfma_f32_16x16x32_bf16 v[90:93], v[164:167], v[204:207], v[90:93]
	v_mfma_f32_16x16x32_bf16 v[82:85], v[150:153], v[212:215], v[82:85]
	v_mfma_f32_16x16x32_bf16 v[74:77], v[164:167], v[212:215], v[74:77]
	v_mfma_f32_16x16x32_bf16 v[118:121], v[168:171], v[184:187], v[118:121]
	v_mfma_f32_16x16x32_bf16 v[110:113], v[176:179], v[184:187], v[110:113]
	v_mfma_f32_16x16x32_bf16 v[102:105], v[168:171], v[192:195], v[102:105]
	v_mfma_f32_16x16x32_bf16 v[94:97], v[176:179], v[192:195], v[94:97]
	v_mfma_f32_16x16x32_bf16 v[86:89], v[168:171], v[200:203], v[86:89]
	v_mfma_f32_16x16x32_bf16 v[78:81], v[176:179], v[200:203], v[78:81]
	v_mfma_f32_16x16x32_bf16 v[70:73], v[168:171], v[208:211], v[70:73]
	v_mfma_f32_16x16x32_bf16 v[66:69], v[176:179], v[208:211], v[66:69]
	v_mfma_f32_16x16x32_bf16 v[118:121], v[172:175], v[188:191], v[118:121]
	v_mfma_f32_16x16x32_bf16 v[110:113], v[180:183], v[188:191], v[110:113]
	v_mfma_f32_16x16x32_bf16 v[102:105], v[172:175], v[196:199], v[102:105]
	v_mfma_f32_16x16x32_bf16 v[94:97], v[180:183], v[196:199], v[94:97]
	v_mfma_f32_16x16x32_bf16 v[86:89], v[172:175], v[204:207], v[86:89]
	v_mfma_f32_16x16x32_bf16 v[78:81], v[180:183], v[204:207], v[78:81]
	v_mfma_f32_16x16x32_bf16 v[70:73], v[172:175], v[212:215], v[70:73]
	v_mfma_f32_16x16x32_bf16 v[66:69], v[180:183], v[212:215], v[66:69]
	s_barrier
	s_add_i32 s18, s64, s52
	v_lshl_add_u64 v[216:217], s[44:45], 0, v[134:135]
	s_mov_b32 m0, s18
	ds_read_b128 v[184:187], v158 offset:16384
	ds_read_b128 v[188:191], v158 offset:17408
	ds_read_b128 v[192:195], v158 offset:18432
	ds_read_b128 v[196:199], v158 offset:19456
	ds_read_b128 v[200:203], v158 offset:20480
	ds_read_b128 v[204:207], v158 offset:21504
	ds_read_b128 v[208:211], v158 offset:22528
	ds_read_b128 v[212:215], v158 offset:23552
	global_load_lds_dwordx4 v[216:217], off
	s_add_i32 m0, s18, 0x2000
	s_add_u32 s74, s44, 0x40000
	v_lshl_add_u64 v[218:219], s[44:45], 0, v[130:131]
	s_addc_u32 s75, s45, 0
	s_add_i32 s18, s65, s52
	global_load_lds_dwordx4 v[218:219], off
	v_lshl_add_u64 v[220:221], s[74:75], 0, v[134:135]
	s_mov_b32 m0, s18
	v_lshl_add_u64 v[224:225], s[46:47], 0, v[132:133]
	global_load_lds_dwordx4 v[220:221], off
	v_lshl_add_u64 v[220:221], s[74:75], 0, v[130:131]
	s_add_i32 m0, s18, 0x2000
	s_nop 0
	global_load_lds_dwordx4 v[220:221], off
	v_lshl_add_u64 v[220:221], s[46:47], 0, v[136:137]
	s_mov_b32 m0, s41
	s_nop 0
	global_load_lds_dwordx4 v[220:221], off
	s_mov_b32 m0, s53
	s_nop 0
	global_load_lds_dwordx4 v[224:225], off
	s_waitcnt vmcnt(8) lgkmcnt(0)
	s_barrier
; #define PG8_STAGE(bufoff, gbase, voff) do { _Pragma("unroll") for (int _i = 0; _i < 2; ++_i) \
;         __builtin_amdgcn_global_load_lds((const unsigned*)((const char*)(gbase) + (voff)[_i]), (PG8_LAS unsigned*)(lds + (bufoff) + ldsw + _i * 8192), 16, 0, 0); } while (0)
; #define PG8_LDA(dst, b, h) do { _Pragma("unroll") for (int m = 0; m < 4; ++m) _Pragma("unroll") for (int k = 0; k < 2; ++k) dst[m][k] = *(const PG8_LAS bf16x8*)(lds + PG8_SA(b, h) + aoff + m * 2048 + k * 1024); } while (0)
; #define PG8_LDB(dst, b, h) do { _Pragma("unroll") for (int n = 0; n < 2; ++n) _Pragma("unroll") for (int k = 0; k < 2; ++k) dst[n][k] = *(const PG8_LAS bf16x8*)(lds + PG8_SB(b, h) + boff + n * 2048 + k * 1024); } while (0)
; #define PG8_MMA(ai, bj, At, Bt) do { __builtin_amdgcn_s_setprio(1); _Pragma("unroll") for (int m = 0; m < 4; ++m) _Pragma("unroll") for (int n = 0; n < 2; ++n) _Pragma("unroll") for (int k = 0; k < 2; ++k) \
;         acc[ai][bj][m][n] = __builtin_amdgcn_mfma_f32_16x16x32_bf16(Bt[n][k], At[m][k], acc[ai][bj][m][n], 0, 0, 0); __builtin_amdgcn_s_setprio(0); } while (0)
; #define PG8_WAIT_V(n) asm volatile("s_waitcnt vmcnt(" #n ")" ::: "memory")
; #define PG8_WAIT_L(n) asm volatile("s_waitcnt lgkmcnt(" #n ")" ::: "memory")
; #define PG8_BAR __builtin_amdgcn_s_barrier()
; #define PG8_SCHED __builtin_amdgcn_sched_barrier(0)
; template <class Epi, class Sched, bool ALIGN_EPI = false, bool SP2 = false>
; __device__ __forceinline__ void gemm_phase(PG8_LAS unsigned char* lds, const Gemm g, const Sched& S, const Epi& E) {
;     ...
;             PG8_WAIT_V(8); PG8_WAIT_L(0); PG8_BAR; PG8_MMA(1, 0, At, B0); PG8_MMA(1, 1, At, B1); PG8_BAR; PG8_SCHED;
;             PG8_LDB(B0, 1, 0); PG8_LDB(B1, 1, 1); PG8_SCHED; PG8_LDA(At, 1, 0); PG8_STAGE(PG8_SA(0, 1), a2 + hA, voffA);
;             PG8_WAIT_V(8); PG8_WAIT_L(0); PG8_BAR; PG8_MMA(0, 0, At, B0); PG8_MMA(0, 1, At, B1); PG8_BAR; PG8_SCHED;
	v_mfma_f32_16x16x32_bf16 v[62:65], v[146:149], v[184:187], v[62:65]
	v_mfma_f32_16x16x32_bf16 v[58:61], v[160:163], v[184:187], v[58:61]
	v_mfma_f32_16x16x32_bf16 v[50:53], v[146:149], v[192:195], v[50:53]
	v_mfma_f32_16x16x32_bf16 v[42:45], v[160:163], v[192:195], v[42:45]
	v_mfma_f32_16x16x32_bf16 v[34:37], v[146:149], v[200:203], v[34:37]
	v_mfma_f32_16x16x32_bf16 v[26:29], v[160:163], v[200:203], v[26:29]
	v_mfma_f32_16x16x32_bf16 v[18:21], v[146:149], v[208:211], v[18:21]
	v_mfma_f32_16x16x32_bf16 v[10:13], v[160:163], v[208:211], v[10:13]
	v_mfma_f32_16x16x32_bf16 v[62:65], v[150:153], v[188:191], v[62:65]
	v_mfma_f32_16x16x32_bf16 v[58:61], v[164:167], v[188:191], v[58:61]
	v_mfma_f32_16x16x32_bf16 v[50:53], v[150:153], v[196:199], v[50:53]
	v_mfma_f32_16x16x32_bf16 v[42:45], v[164:167], v[196:199], v[42:45]
	v_mfma_f32_16x16x32_bf16 v[34:37], v[150:153], v[204:207], v[34:37]
	v_mfma_f32_16x16x32_bf16 v[26:29], v[164:167], v[204:207], v[26:29]
	v_mfma_f32_16x16x32_bf16 v[18:21], v[150:153], v[212:215], v[18:21]
	v_mfma_f32_16x16x32_bf16 v[10:13], v[164:167], v[212:215], v[10:13]
	v_mfma_f32_16x16x32_bf16 v[54:57], v[168:171], v[184:187], v[54:57]
	v_mfma_f32_16x16x32_bf16 v[46:49], v[176:179], v[184:187], v[46:49]
	v_mfma_f32_16x16x32_bf16 v[38:41], v[168:171], v[192:195], v[38:41]
	v_mfma_f32_16x16x32_bf16 v[30:33], v[176:179], v[192:195], v[30:33]
	v_mfma_f32_16x16x32_bf16 v[22:25], v[168:171], v[200:203], v[22:25]
	v_mfma_f32_16x16x32_bf16 v[14:17], v[176:179], v[200:203], v[14:17]
	v_mfma_f32_16x16x32_bf16 v[6:9], v[168:171], v[208:211], v[6:9]
	v_mfma_f32_16x16x32_bf16 v[2:5], v[176:179], v[208:211], v[2:5]
	v_mfma_f32_16x16x32_bf16 v[54:57], v[172:175], v[188:191], v[54:57]
	v_mfma_f32_16x16x32_bf16 v[46:49], v[180:183], v[188:191], v[46:49]
	v_mfma_f32_16x16x32_bf16 v[38:41], v[172:175], v[196:199], v[38:41]
	v_mfma_f32_16x16x32_bf16 v[30:33], v[180:183], v[196:199], v[30:33]
	v_mfma_f32_16x16x32_bf16 v[22:25], v[172:175], v[204:207], v[22:25]
	v_mfma_f32_16x16x32_bf16 v[14:17], v[180:183], v[204:207], v[14:17]
	v_mfma_f32_16x16x32_bf16 v[6:9], v[172:175], v[212:215], v[6:9]
	v_mfma_f32_16x16x32_bf16 v[2:5], v[180:183], v[212:215], v[2:5]
	s_barrier
	s_add_i32 s18, 0, 0x18000
	v_add_u32_e32 v159, s18, v154
	s_add_i32 s19, 0, 0x1c000
	ds_read_b128 v[146:149], v159
	ds_read_b128 v[150:153], v159 offset:1024
	ds_read_b128 v[160:163], v159 offset:2048
	ds_read_b128 v[164:167], v159 offset:3072
	v_add_u32_e32 v159, s19, v154
	ds_read_b128 v[168:171], v159
	ds_read_b128 v[172:175], v159 offset:1024
	ds_read_b128 v[176:179], v159 offset:2048
	ds_read_b128 v[180:183], v159 offset:3072
	s_add_u32 s46, s46, 0x40000
	s_addc_u32 s47, s47, 0
	s_mov_b32 m0, s58
	v_lshl_add_u64 v[226:227], s[46:47], 0, v[136:137]
	ds_read_b128 v[184:187], v158 offset:32768
	ds_read_b128 v[188:191], v158 offset:33792
	ds_read_b128 v[192:195], v158 offset:34816
	ds_read_b128 v[196:199], v158 offset:35840
	ds_read_b128 v[200:203], v158 offset:36864
	ds_read_b128 v[204:207], v158 offset:37888
	ds_read_b128 v[208:211], v158 offset:38912
	ds_read_b128 v[212:215], v158 offset:39936
	global_load_lds_dwordx4 v[226:227], off
	v_lshl_add_u64 v[226:227], s[46:47], 0, v[132:133]
	s_mov_b32 m0, s59
	s_nop 0
	global_load_lds_dwordx4 v[226:227], off
	s_waitcnt vmcnt(8) lgkmcnt(0)
	s_barrier
	v_mfma_f32_16x16x32_bf16 v[126:129], v[146:149], v[184:187], v[126:129]
	v_mfma_f32_16x16x32_bf16 v[122:125], v[160:163], v[184:187], v[122:125]
	v_mfma_f32_16x16x32_bf16 v[114:117], v[146:149], v[192:195], v[114:117]
	v_mfma_f32_16x16x32_bf16 v[106:109], v[160:163], v[192:195], v[106:109]
	v_mfma_f32_16x16x32_bf16 v[98:101], v[146:149], v[200:203], v[98:101]
	v_mfma_f32_16x16x32_bf16 v[90:93], v[160:163], v[200:203], v[90:93]
	v_mfma_f32_16x16x32_bf16 v[82:85], v[146:149], v[208:211], v[82:85]
	v_mfma_f32_16x16x32_bf16 v[74:77], v[160:163], v[208:211], v[74:77]
	v_mfma_f32_16x16x32_bf16 v[126:129], v[150:153], v[188:191], v[126:129]
	v_mfma_f32_16x16x32_bf16 v[122:125], v[164:167], v[188:191], v[122:125]
	v_mfma_f32_16x16x32_bf16 v[114:117], v[150:153], v[196:199], v[114:117]
	v_mfma_f32_16x16x32_bf16 v[106:109], v[164:167], v[196:199], v[106:109]
	v_mfma_f32_16x16x32_bf16 v[98:101], v[150:153], v[204:207], v[98:101]
	v_mfma_f32_16x16x32_bf16 v[90:93], v[164:167], v[204:207], v[90:93]
	v_mfma_f32_16x16x32_bf16 v[82:85], v[150:153], v[212:215], v[82:85]
	v_mfma_f32_16x16x32_bf16 v[74:77], v[164:167], v[212:215], v[74:77]
	v_mfma_f32_16x16x32_bf16 v[118:121], v[168:171], v[184:187], v[118:121]
	v_mfma_f32_16x16x32_bf16 v[110:113], v[176:179], v[184:187], v[110:113]
	v_mfma_f32_16x16x32_bf16 v[102:105], v[168:171], v[192:195], v[102:105]
	v_mfma_f32_16x16x32_bf16 v[94:97], v[176:179], v[192:195], v[94:97]
	v_mfma_f32_16x16x32_bf16 v[86:89], v[168:171], v[200:203], v[86:89]
	v_mfma_f32_16x16x32_bf16 v[78:81], v[176:179], v[200:203], v[78:81]
	v_mfma_f32_16x16x32_bf16 v[70:73], v[168:171], v[208:211], v[70:73]
	v_mfma_f32_16x16x32_bf16 v[66:69], v[176:179], v[208:211], v[66:69]
	v_mfma_f32_16x16x32_bf16 v[118:121], v[172:175], v[188:191], v[118:121]
	v_mfma_f32_16x16x32_bf16 v[110:113], v[180:183], v[188:191], v[110:113]
	v_mfma_f32_16x16x32_bf16 v[102:105], v[172:175], v[196:199], v[102:105]
	v_mfma_f32_16x16x32_bf16 v[94:97], v[180:183], v[196:199], v[94:97]
	v_mfma_f32_16x16x32_bf16 v[86:89], v[172:175], v[204:207], v[86:89]
	v_mfma_f32_16x16x32_bf16 v[78:81], v[180:183], v[204:207], v[78:81]
	v_mfma_f32_16x16x32_bf16 v[70:73], v[172:175], v[212:215], v[70:73]
	v_mfma_f32_16x16x32_bf16 v[66:69], v[180:183], v[212:215], v[66:69]
	s_barrier
; #define PG8_STAGE(bufoff, gbase, voff) do { _Pragma("unroll") for (int _i = 0; _i < 2; ++_i) \
;         __builtin_amdgcn_global_load_lds((const unsigned*)((const char*)(gbase) + (voff)[_i]), (PG8_LAS unsigned*)(lds + (bufoff) + ldsw + _i * 8192), 16, 0, 0); } while (0)
; #define PG8_LDA(dst, b, h) do { _Pragma("unroll") for (int m = 0; m < 4; ++m) _Pragma("unroll") for (int k = 0; k < 2; ++k) dst[m][k] = *(const PG8_LAS bf16x8*)(lds + PG8_SA(b, h) + aoff + m * 2048 + k * 1024); } while (0)
; #define PG8_MMA(ai, bj, At, Bt) do { __builtin_amdgcn_s_setprio(1); _Pragma("unroll") for (int m = 0; m < 4; ++m) _Pragma("unroll") for (int n = 0; n < 2; ++n) _Pragma("unroll") for (int k = 0; k < 2; ++k) \
;         acc[ai][bj][m][n] = __builtin_amdgcn_mfma_f32_16x16x32_bf16(Bt[n][k], At[m][k], acc[ai][bj][m][n], 0, 0, 0); __builtin_amdgcn_s_setprio(0); } while (0)
; #define PG8_WAIT_V(n) asm volatile("s_waitcnt vmcnt(" #n ")" ::: "memory")
; #define PG8_WAIT_L(n) asm volatile("s_waitcnt lgkmcnt(" #n ")" ::: "memory")
; #define PG8_BAR __builtin_amdgcn_s_barrier()
; #define PG8_SCHED __builtin_amdgcn_sched_barrier(0)
; template <class Epi, class Sched, bool ALIGN_EPI = false, bool SP2 = false>
; __device__ __forceinline__ void gemm_phase(PG8_LAS unsigned char* lds, const Gemm g, const Sched& S, const Epi& E) {
;     ...
;             PG8_LDA(At, 1, 1); PG8_STAGE(PG8_SB(1, 0), b3, voffB); PG8_STAGE(PG8_SB(1, 1), b3 + hB, voffB); PG8_STAGE(PG8_SA(1, 0), a3, voffA);
;             PG8_WAIT_V(8); PG8_WAIT_L(0); PG8_BAR; PG8_MMA(1, 0, At, B0); PG8_MMA(1, 1, At, B1); PG8_BAR; PG8_SCHED;
;     ...
;         if constexpr (ALIGN_EPI) { if (wr == 0) PG8_BAR; }
	s_add_i32 s18, s18, s52
	v_lshl_add_u64 v[216:217], v[216:217], 0, s[8:9]
	s_mov_b32 m0, s18
	ds_read_b128 v[184:187], v158 offset:49152
	ds_read_b128 v[188:191], v158 offset:50176
	ds_read_b128 v[192:195], v158 offset:51200
	ds_read_b128 v[196:199], v158 offset:52224
	ds_read_b128 v[200:203], v158 offset:53248
	ds_read_b128 v[204:207], v158 offset:54272
	ds_read_b128 v[208:211], v158 offset:55296
	ds_read_b128 v[212:215], v158 offset:56320
	global_load_lds_dwordx4 v[216:217], off
	s_add_i32 m0, s18, 0x2000
	s_add_u32 s44, s44, 0x40080
	v_lshl_add_u64 v[216:217], v[218:219], 0, s[8:9]
	s_addc_u32 s45, s45, 0
	s_add_i32 s18, s19, s52
	global_load_lds_dwordx4 v[216:217], off
	v_lshl_add_u64 v[216:217], s[44:45], 0, v[134:135]
	s_mov_b32 m0, s18
	s_nop 0
	global_load_lds_dwordx4 v[216:217], off
	v_lshl_add_u64 v[216:217], s[44:45], 0, v[130:131]
	s_add_i32 m0, s18, 0x2000
	s_nop 0
	global_load_lds_dwordx4 v[216:217], off
	v_lshl_add_u64 v[216:217], v[220:221], 0, s[8:9]
	s_mov_b32 m0, s60
	s_nop 0
	global_load_lds_dwordx4 v[216:217], off
	v_lshl_add_u64 v[216:217], v[224:225], 0, s[8:9]
	s_mov_b32 m0, s61
	s_nop 0
	global_load_lds_dwordx4 v[216:217], off
	s_waitcnt vmcnt(8) lgkmcnt(0)
	s_barrier
	v_mfma_f32_16x16x32_bf16 v[62:65], v[146:149], v[184:187], v[62:65]
	v_mfma_f32_16x16x32_bf16 v[58:61], v[160:163], v[184:187], v[58:61]
	v_mfma_f32_16x16x32_bf16 v[50:53], v[146:149], v[192:195], v[50:53]
	v_mfma_f32_16x16x32_bf16 v[42:45], v[160:163], v[192:195], v[42:45]
	v_mfma_f32_16x16x32_bf16 v[34:37], v[146:149], v[200:203], v[34:37]
	v_mfma_f32_16x16x32_bf16 v[26:29], v[160:163], v[200:203], v[26:29]
	v_mfma_f32_16x16x32_bf16 v[18:21], v[146:149], v[208:211], v[18:21]
	v_mfma_f32_16x16x32_bf16 v[10:13], v[160:163], v[208:211], v[10:13]
	v_mfma_f32_16x16x32_bf16 v[62:65], v[150:153], v[188:191], v[62:65]
	v_mfma_f32_16x16x32_bf16 v[58:61], v[164:167], v[188:191], v[58:61]
	v_mfma_f32_16x16x32_bf16 v[50:53], v[150:153], v[196:199], v[50:53]
	v_mfma_f32_16x16x32_bf16 v[42:45], v[164:167], v[196:199], v[42:45]
	v_mfma_f32_16x16x32_bf16 v[34:37], v[150:153], v[204:207], v[34:37]
	v_mfma_f32_16x16x32_bf16 v[26:29], v[164:167], v[204:207], v[26:29]
	v_mfma_f32_16x16x32_bf16 v[18:21], v[150:153], v[212:215], v[18:21]
	v_mfma_f32_16x16x32_bf16 v[10:13], v[164:167], v[212:215], v[10:13]
	v_mfma_f32_16x16x32_bf16 v[54:57], v[168:171], v[184:187], v[54:57]
	v_mfma_f32_16x16x32_bf16 v[46:49], v[176:179], v[184:187], v[46:49]
	v_mfma_f32_16x16x32_bf16 v[38:41], v[168:171], v[192:195], v[38:41]
	v_mfma_f32_16x16x32_bf16 v[30:33], v[176:179], v[192:195], v[30:33]
	v_mfma_f32_16x16x32_bf16 v[22:25], v[168:171], v[200:203], v[22:25]
	v_mfma_f32_16x16x32_bf16 v[14:17], v[176:179], v[200:203], v[14:17]
	v_mfma_f32_16x16x32_bf16 v[6:9], v[168:171], v[208:211], v[6:9]
	v_mfma_f32_16x16x32_bf16 v[2:5], v[176:179], v[208:211], v[2:5]
	v_mfma_f32_16x16x32_bf16 v[54:57], v[172:175], v[188:191], v[54:57]
	v_mfma_f32_16x16x32_bf16 v[46:49], v[180:183], v[188:191], v[46:49]
	v_mfma_f32_16x16x32_bf16 v[38:41], v[172:175], v[196:199], v[38:41]
	v_mfma_f32_16x16x32_bf16 v[30:33], v[180:183], v[196:199], v[30:33]
	v_mfma_f32_16x16x32_bf16 v[22:25], v[172:175], v[204:207], v[22:25]
	v_mfma_f32_16x16x32_bf16 v[14:17], v[180:183], v[204:207], v[14:17]
	v_mfma_f32_16x16x32_bf16 v[6:9], v[172:175], v[212:215], v[6:9]
	v_mfma_f32_16x16x32_bf16 v[2:5], v[180:183], v[212:215], v[2:5]
	s_barrier
	s_add_i32 s72, s72, 2
	s_add_u32 s42, s42, 0x100
	s_addc_u32 s43, s43, 0
	s_add_u32 s70, s70, 0x100
	s_addc_u32 s71, s71, 0
	s_cmp_gt_u32 s72, 13
	s_cbranch_scc0 .LBB0_868
	s_and_b64 vcc, exec, s[14:15]
	s_cbranch_vccz .LBB0_871
	s_barrier

; #define PG8_STAGE(bufoff, gbase, voff) do { _Pragma("unroll") for (int _i = 0; _i < 2; ++_i) \
;         __builtin_amdgcn_global_load_lds((const unsigned*)((const char*)(gbase) + (voff)[_i]), (PG8_LAS unsigned*)(lds + (bufoff) + ldsw + _i * 8192), 16, 0, 0); } while (0)
; #define PG8_LDA(dst, b, h) do { _Pragma("unroll") for (int m = 0; m < 4; ++m) _Pragma("unroll") for (int k = 0; k < 2; ++k) dst[m][k] = *(const PG8_LAS bf16x8*)(lds + PG8_SA(b, h) + aoff + m * 2048 + k * 1024); } while (0)
; #define PG8_LDB(dst, b, h) do { _Pragma("unroll") for (int n = 0; n < 2; ++n) _Pragma("unroll") for (int k = 0; k < 2; ++k) dst[n][k] = *(const PG8_LAS bf16x8*)(lds + PG8_SB(b, h) + boff + n * 2048 + k * 1024); } while (0)
; #define PG8_MMA(ai, bj, At, Bt) do { __builtin_amdgcn_s_setprio(1); _Pragma("unroll") for (int m = 0; m < 4; ++m) _Pragma("unroll") for (int n = 0; n < 2; ++n) _Pragma("unroll") for (int k = 0; k < 2; ++k) \
;         acc[ai][bj][m][n] = __builtin_amdgcn_mfma_f32_16x16x32_bf16(Bt[n][k], At[m][k], acc[ai][bj][m][n], 0, 0, 0); __builtin_amdgcn_s_setprio(0); } while (0)
; #define PG8_WAIT_V(n) asm volatile("s_waitcnt vmcnt(" #n ")" ::: "memory")
; #define PG8_WAIT_L(n) asm volatile("s_waitcnt lgkmcnt(" #n ")" ::: "memory")
; template <class Epi, class Sched, bool ALIGN_EPI = false, bool SP2 = false>
; __device__ __forceinline__ void gemm_phase(PG8_LAS unsigned char* lds, const Gemm g, const Sched& S, const Epi& E) {
;     ...
;             const bool last = (t == nt - 2);
;             const char* a1 = cA + (size_t)(t + 1) * kstep;
;             const char* a2 = last ? nA : cA + (size_t)(t + 2) * kstep; const char* b2 = last ? nB : cB + (size_t)(t + 2) * kstep;
;             const char* a3 = a2 + kstep; const char* b3 = b2 + kstep;
;             if (last && has_next) S.a_ready(nxt);
;             if constexpr (SP2) {
;             PG8_LDB(B0, 0, 0); PG8_LDB(B1, 0, 1); PG8_SCHED; PG8_LDA(At, 0, 0); PG8_STAGE(PG8_SA(1, 1), a1 + hA, voffA);
;             PG8_WAIT_V(8); PG8_WAIT_L(0); PG8_BAR; PG8_MMA(0, 0, At, B0); PG8_MMA(0, 1, At, B1); PG8_BAR; PG8_SCHED;
;             PG8_LDA(At, 0, 1); PG8_STAGE(PG8_SB(0, 0), b2, voffB); PG8_STAGE(PG8_SB(0, 1), b2 + hB, voffB); PG8_STAGE(PG8_SA(0, 0), a2, voffA);
;             PG8_WAIT_V(8); PG8_WAIT_L(0); PG8_BAR; PG8_MMA(1, 0, At, B0); PG8_MMA(1, 1, At, B1); PG8_BAR; PG8_SCHED;
.LBB0_888:
	ds_read_b128 v[130:133], v172
	ds_read_b128 v[134:137], v172 offset:1024
	ds_read_b128 v[138:141], v172 offset:2048
	ds_read_b128 v[142:145], v172 offset:3072
	ds_read_b128 v[162:165], v173
	ds_read_b128 v[166:169], v173 offset:1024
	ds_read_b128 v[176:179], v173 offset:2048
	ds_read_b128 v[180:183], v173 offset:3072
	s_add_u32 s18, s44, 0xfff80080
	s_addc_u32 s19, s45, -1
	s_cmp_eq_u32 s74, 28
	s_cselect_b32 s49, s25, s19
	s_cselect_b32 s48, s70, s18
	s_cselect_b32 s47, s23, s73
	s_cselect_b32 s46, s71, s72
	v_lshl_add_u64 v[216:217], s[44:45], 0, v[154:155]
	s_add_i32 m0, s43, 0xc000
	ds_read_b128 v[184:187], v174
	ds_read_b128 v[188:191], v174 offset:1024
	ds_read_b128 v[192:195], v174 offset:2048
	ds_read_b128 v[196:199], v174 offset:3072
	ds_read_b128 v[200:203], v174 offset:4096
	ds_read_b128 v[204:207], v174 offset:5120
	ds_read_b128 v[208:211], v174 offset:6144
	ds_read_b128 v[212:215], v174 offset:7168
	global_load_lds_dwordx4 v[216:217], off
	v_lshl_add_u64 v[216:217], s[44:45], 0, v[156:157]
	s_add_i32 m0, s43, 0xe000
	s_nop 0
	global_load_lds_dwordx4 v[216:217], off
	s_waitcnt vmcnt(8) lgkmcnt(0)
	s_barrier
	v_mfma_f32_16x16x32_bf16 v[126:129], v[130:133], v[184:187], v[126:129]
	v_mfma_f32_16x16x32_bf16 v[122:125], v[138:141], v[184:187], v[122:125]
	v_mfma_f32_16x16x32_bf16 v[110:113], v[130:133], v[192:195], v[110:113]
	v_mfma_f32_16x16x32_bf16 v[106:109], v[138:141], v[192:195], v[106:109]
	v_mfma_f32_16x16x32_bf16 v[94:97], v[130:133], v[200:203], v[94:97]
	v_mfma_f32_16x16x32_bf16 v[90:93], v[138:141], v[200:203], v[90:93]
	v_mfma_f32_16x16x32_bf16 v[78:81], v[130:133], v[208:211], v[78:81]
	v_mfma_f32_16x16x32_bf16 v[74:77], v[138:141], v[208:211], v[74:77]
	v_mfma_f32_16x16x32_bf16 v[126:129], v[134:137], v[188:191], v[126:129]
	v_mfma_f32_16x16x32_bf16 v[122:125], v[142:145], v[188:191], v[122:125]
	v_mfma_f32_16x16x32_bf16 v[110:113], v[134:137], v[196:199], v[110:113]
	v_mfma_f32_16x16x32_bf16 v[106:109], v[142:145], v[196:199], v[106:109]
	v_mfma_f32_16x16x32_bf16 v[94:97], v[134:137], v[204:207], v[94:97]
	v_mfma_f32_16x16x32_bf16 v[90:93], v[142:145], v[204:207], v[90:93]
	v_mfma_f32_16x16x32_bf16 v[78:81], v[134:137], v[212:215], v[78:81]
	v_mfma_f32_16x16x32_bf16 v[74:77], v[142:145], v[212:215], v[74:77]
	v_mfma_f32_16x16x32_bf16 v[118:121], v[162:165], v[184:187], v[118:121]
	v_mfma_f32_16x16x32_bf16 v[114:117], v[176:179], v[184:187], v[114:117]
	v_mfma_f32_16x16x32_bf16 v[102:105], v[162:165], v[192:195], v[102:105]
	v_mfma_f32_16x16x32_bf16 v[98:101], v[176:179], v[192:195], v[98:101]
	v_mfma_f32_16x16x32_bf16 v[86:89], v[162:165], v[200:203], v[86:89]
	v_mfma_f32_16x16x32_bf16 v[82:85], v[176:179], v[200:203], v[82:85]
	v_mfma_f32_16x16x32_bf16 v[70:73], v[162:165], v[208:211], v[70:73]
	v_mfma_f32_16x16x32_bf16 v[66:69], v[176:179], v[208:211], v[66:69]
	v_mfma_f32_16x16x32_bf16 v[118:121], v[166:169], v[188:191], v[118:121]
	v_mfma_f32_16x16x32_bf16 v[114:117], v[180:183], v[188:191], v[114:117]
	v_mfma_f32_16x16x32_bf16 v[102:105], v[166:169], v[196:199], v[102:105]
	v_mfma_f32_16x16x32_bf16 v[98:101], v[180:183], v[196:199], v[98:101]
	v_mfma_f32_16x16x32_bf16 v[86:89], v[166:169], v[204:207], v[86:89]
	v_mfma_f32_16x16x32_bf16 v[82:85], v[180:183], v[204:207], v[82:85]
	v_mfma_f32_16x16x32_bf16 v[70:73], v[166:169], v[212:215], v[70:73]
	v_mfma_f32_16x16x32_bf16 v[66:69], v[180:183], v[212:215], v[66:69]
	s_barrier
	s_add_i32 s18, s66, s58
	v_lshl_add_u64 v[216:217], s[46:47], 0, v[150:151]
	s_mov_b32 m0, s18
	ds_read_b128 v[184:187], v174 offset:16384
	ds_read_b128 v[188:191], v174 offset:17408
	ds_read_b128 v[192:195], v174 offset:18432
	ds_read_b128 v[196:199], v174 offset:19456
	ds_read_b128 v[200:203], v174 offset:20480
	ds_read_b128 v[204:207], v174 offset:21504
	ds_read_b128 v[208:211], v174 offset:22528
	ds_read_b128 v[212:215], v174 offset:23552
	global_load_lds_dwordx4 v[216:217], off
	s_add_i32 m0, s18, 0x2000
	s_add_u32 s76, s46, 0x80000
	v_lshl_add_u64 v[218:219], s[46:47], 0, v[146:147]
	s_addc_u32 s77, s47, 0
	s_add_i32 s18, s67, s58
	global_load_lds_dwordx4 v[218:219], off
	v_lshl_add_u64 v[220:221], s[76:77], 0, v[150:151]
	s_mov_b32 m0, s18
	v_lshl_add_u64 v[224:225], s[48:49], 0, v[148:149]
	global_load_lds_dwordx4 v[220:221], off
	v_lshl_add_u64 v[220:221], s[76:77], 0, v[146:147]
	s_add_i32 m0, s18, 0x2000
	s_nop 0
	global_load_lds_dwordx4 v[220:221], off
	v_lshl_add_u64 v[220:221], s[48:49], 0, v[152:153]
	s_mov_b32 m0, s43
	s_nop 0
	global_load_lds_dwordx4 v[220:221], off
	s_mov_b32 m0, s59
	s_nop 0
	global_load_lds_dwordx4 v[224:225], off
	s_waitcnt vmcnt(8) lgkmcnt(0)
	s_barrier
; #define PG8_STAGE(bufoff, gbase, voff) do { _Pragma("unroll") for (int _i = 0; _i < 2; ++_i) \
;         __builtin_amdgcn_global_load_lds((const unsigned*)((const char*)(gbase) + (voff)[_i]), (PG8_LAS unsigned*)(lds + (bufoff) + ldsw + _i * 8192), 16, 0, 0); } while (0)
; #define PG8_LDA(dst, b, h) do { _Pragma("unroll") for (int m = 0; m < 4; ++m) _Pragma("unroll") for (int k = 0; k < 2; ++k) dst[m][k] = *(const PG8_LAS bf16x8*)(lds + PG8_SA(b, h) + aoff + m * 2048 + k * 1024); } while (0)
; #define PG8_LDB(dst, b, h) do { _Pragma("unroll") for (int n = 0; n < 2; ++n) _Pragma("unroll") for (int k = 0; k < 2; ++k) dst[n][k] = *(const PG8_LAS bf16x8*)(lds + PG8_SB(b, h) + boff + n * 2048 + k * 1024); } while (0)
; #define PG8_MMA(ai, bj, At, Bt) do { __builtin_amdgcn_s_setprio(1); _Pragma("unroll") for (int m = 0; m < 4; ++m) _Pragma("unroll") for (int n = 0; n < 2; ++n) _Pragma("unroll") for (int k = 0; k < 2; ++k) \
;         acc[ai][bj][m][n] = __builtin_amdgcn_mfma_f32_16x16x32_bf16(Bt[n][k], At[m][k], acc[ai][bj][m][n], 0, 0, 0); __builtin_amdgcn_s_setprio(0); } while (0)
; #define PG8_WAIT_V(n) asm volatile("s_waitcnt vmcnt(" #n ")" ::: "memory")
; #define PG8_WAIT_L(n) asm volatile("s_waitcnt lgkmcnt(" #n ")" ::: "memory")
; #define PG8_BAR __builtin_amdgcn_s_barrier()
; #define PG8_SCHED __builtin_amdgcn_sched_barrier(0)
; template <class Epi, class Sched, bool ALIGN_EPI = false, bool SP2 = false>
; __device__ __forceinline__ void gemm_phase(PG8_LAS unsigned char* lds, const Gemm g, const Sched& S, const Epi& E) {
;     ...
;             PG8_WAIT_V(8); PG8_WAIT_L(0); PG8_BAR; PG8_MMA(1, 0, At, B0); PG8_MMA(1, 1, At, B1); PG8_BAR; PG8_SCHED;
;             PG8_LDB(B0, 1, 0); PG8_LDB(B1, 1, 1); PG8_SCHED; PG8_LDA(At, 1, 0); PG8_STAGE(PG8_SA(0, 1), a2 + hA, voffA);
;             PG8_WAIT_V(8); PG8_WAIT_L(0); PG8_BAR; PG8_MMA(0, 0, At, B0); PG8_MMA(0, 1, At, B1); PG8_BAR; PG8_SCHED;
	v_mfma_f32_16x16x32_bf16 v[62:65], v[130:133], v[184:187], v[62:65]
	v_mfma_f32_16x16x32_bf16 v[58:61], v[138:141], v[184:187], v[58:61]
	v_mfma_f32_16x16x32_bf16 v[46:49], v[130:133], v[192:195], v[46:49]
	v_mfma_f32_16x16x32_bf16 v[42:45], v[138:141], v[192:195], v[42:45]
	v_mfma_f32_16x16x32_bf16 v[30:33], v[130:133], v[200:203], v[30:33]
	v_mfma_f32_16x16x32_bf16 v[26:29], v[138:141], v[200:203], v[26:29]
	v_mfma_f32_16x16x32_bf16 v[14:17], v[130:133], v[208:211], v[14:17]
	v_mfma_f32_16x16x32_bf16 v[10:13], v[138:141], v[208:211], v[10:13]
	v_mfma_f32_16x16x32_bf16 v[62:65], v[134:137], v[188:191], v[62:65]
	v_mfma_f32_16x16x32_bf16 v[58:61], v[142:145], v[188:191], v[58:61]
	v_mfma_f32_16x16x32_bf16 v[46:49], v[134:137], v[196:199], v[46:49]
	v_mfma_f32_16x16x32_bf16 v[42:45], v[142:145], v[196:199], v[42:45]
	v_mfma_f32_16x16x32_bf16 v[30:33], v[134:137], v[204:207], v[30:33]
	v_mfma_f32_16x16x32_bf16 v[26:29], v[142:145], v[204:207], v[26:29]
	v_mfma_f32_16x16x32_bf16 v[14:17], v[134:137], v[212:215], v[14:17]
	v_mfma_f32_16x16x32_bf16 v[10:13], v[142:145], v[212:215], v[10:13]
	v_mfma_f32_16x16x32_bf16 v[54:57], v[162:165], v[184:187], v[54:57]
	v_mfma_f32_16x16x32_bf16 v[50:53], v[176:179], v[184:187], v[50:53]
	v_mfma_f32_16x16x32_bf16 v[38:41], v[162:165], v[192:195], v[38:41]
	v_mfma_f32_16x16x32_bf16 v[34:37], v[176:179], v[192:195], v[34:37]
	v_mfma_f32_16x16x32_bf16 v[22:25], v[162:165], v[200:203], v[22:25]
	v_mfma_f32_16x16x32_bf16 v[18:21], v[176:179], v[200:203], v[18:21]
	v_mfma_f32_16x16x32_bf16 v[6:9], v[162:165], v[208:211], v[6:9]
	v_mfma_f32_16x16x32_bf16 v[2:5], v[176:179], v[208:211], v[2:5]
	v_mfma_f32_16x16x32_bf16 v[54:57], v[166:169], v[188:191], v[54:57]
	v_mfma_f32_16x16x32_bf16 v[50:53], v[180:183], v[188:191], v[50:53]
	v_mfma_f32_16x16x32_bf16 v[38:41], v[166:169], v[196:199], v[38:41]
	v_mfma_f32_16x16x32_bf16 v[34:37], v[180:183], v[196:199], v[34:37]
	v_mfma_f32_16x16x32_bf16 v[22:25], v[166:169], v[204:207], v[22:25]
	v_mfma_f32_16x16x32_bf16 v[18:21], v[180:183], v[204:207], v[18:21]
	v_mfma_f32_16x16x32_bf16 v[6:9], v[166:169], v[212:215], v[6:9]
	v_mfma_f32_16x16x32_bf16 v[2:5], v[180:183], v[212:215], v[2:5]
	s_barrier
	s_add_i32 s18, 0, 0x18000
	s_add_i32 s19, 0, 0x1c000
	v_add_u32_e32 v142, s18, v170
	v_add_u32_e32 v175, s19, v170
	ds_read_b128 v[130:133], v142
	ds_read_b128 v[134:137], v142 offset:1024
	ds_read_b128 v[138:141], v142 offset:2048
	ds_read_b128 v[142:145], v142 offset:3072
	ds_read_b128 v[162:165], v175
	ds_read_b128 v[166:169], v175 offset:1024
	ds_read_b128 v[176:179], v175 offset:2048
	ds_read_b128 v[180:183], v175 offset:3072
	s_add_u32 s48, s48, 0x80000
	s_addc_u32 s49, s49, 0
	s_mov_b32 m0, s60
	v_lshl_add_u64 v[226:227], s[48:49], 0, v[152:153]
	ds_read_b128 v[184:187], v174 offset:32768
	ds_read_b128 v[188:191], v174 offset:33792
	ds_read_b128 v[192:195], v174 offset:34816
	ds_read_b128 v[196:199], v174 offset:35840
	ds_read_b128 v[200:203], v174 offset:36864
	ds_read_b128 v[204:207], v174 offset:37888
	ds_read_b128 v[208:211], v174 offset:38912
	ds_read_b128 v[212:215], v174 offset:39936
	global_load_lds_dwordx4 v[226:227], off
	v_lshl_add_u64 v[226:227], s[48:49], 0, v[148:149]
	s_mov_b32 m0, s61
	s_nop 0
	global_load_lds_dwordx4 v[226:227], off
	s_waitcnt vmcnt(8) lgkmcnt(0)
	s_barrier
	v_mfma_f32_16x16x32_bf16 v[126:129], v[130:133], v[184:187], v[126:129]
	v_mfma_f32_16x16x32_bf16 v[122:125], v[138:141], v[184:187], v[122:125]
	v_mfma_f32_16x16x32_bf16 v[110:113], v[130:133], v[192:195], v[110:113]
	v_mfma_f32_16x16x32_bf16 v[106:109], v[138:141], v[192:195], v[106:109]
	v_mfma_f32_16x16x32_bf16 v[94:97], v[130:133], v[200:203], v[94:97]
	v_mfma_f32_16x16x32_bf16 v[90:93], v[138:141], v[200:203], v[90:93]
	v_mfma_f32_16x16x32_bf16 v[78:81], v[130:133], v[208:211], v[78:81]
	v_mfma_f32_16x16x32_bf16 v[74:77], v[138:141], v[208:211], v[74:77]
	v_mfma_f32_16x16x32_bf16 v[126:129], v[134:137], v[188:191], v[126:129]
	v_mfma_f32_16x16x32_bf16 v[122:125], v[142:145], v[188:191], v[122:125]
	v_mfma_f32_16x16x32_bf16 v[110:113], v[134:137], v[196:199], v[110:113]
	v_mfma_f32_16x16x32_bf16 v[106:109], v[142:145], v[196:199], v[106:109]
	v_mfma_f32_16x16x32_bf16 v[94:97], v[134:137], v[204:207], v[94:97]
	v_mfma_f32_16x16x32_bf16 v[90:93], v[142:145], v[204:207], v[90:93]
	v_mfma_f32_16x16x32_bf16 v[78:81], v[134:137], v[212:215], v[78:81]
	v_mfma_f32_16x16x32_bf16 v[74:77], v[142:145], v[212:215], v[74:77]
	v_mfma_f32_16x16x32_bf16 v[118:121], v[162:165], v[184:187], v[118:121]
	v_mfma_f32_16x16x32_bf16 v[114:117], v[176:179], v[184:187], v[114:117]
	v_mfma_f32_16x16x32_bf16 v[102:105], v[162:165], v[192:195], v[102:105]
	v_mfma_f32_16x16x32_bf16 v[98:101], v[176:179], v[192:195], v[98:101]
	v_mfma_f32_16x16x32_bf16 v[86:89], v[162:165], v[200:203], v[86:89]
	v_mfma_f32_16x16x32_bf16 v[82:85], v[176:179], v[200:203], v[82:85]
	v_mfma_f32_16x16x32_bf16 v[70:73], v[162:165], v[208:211], v[70:73]
	v_mfma_f32_16x16x32_bf16 v[66:69], v[176:179], v[208:211], v[66:69]
	v_mfma_f32_16x16x32_bf16 v[118:121], v[166:169], v[188:191], v[118:121]
	v_mfma_f32_16x16x32_bf16 v[114:117], v[180:183], v[188:191], v[114:117]
	v_mfma_f32_16x16x32_bf16 v[102:105], v[166:169], v[196:199], v[102:105]
	v_mfma_f32_16x16x32_bf16 v[98:101], v[180:183], v[196:199], v[98:101]
	v_mfma_f32_16x16x32_bf16 v[86:89], v[166:169], v[204:207], v[86:89]
	v_mfma_f32_16x16x32_bf16 v[82:85], v[180:183], v[204:207], v[82:85]
	v_mfma_f32_16x16x32_bf16 v[70:73], v[166:169], v[212:215], v[70:73]
	v_mfma_f32_16x16x32_bf16 v[66:69], v[180:183], v[212:215], v[66:69]
	s_barrier
; #define PG8_STAGE(bufoff, gbase, voff) do { _Pragma("unroll") for (int _i = 0; _i < 2; ++_i) \
;         __builtin_amdgcn_global_load_lds((const unsigned*)((const char*)(gbase) + (voff)[_i]), (PG8_LAS unsigned*)(lds + (bufoff) + ldsw + _i * 8192), 16, 0, 0); } while (0)
; #define PG8_LDA(dst, b, h) do { _Pragma("unroll") for (int m = 0; m < 4; ++m) _Pragma("unroll") for (int k = 0; k < 2; ++k) dst[m][k] = *(const PG8_LAS bf16x8*)(lds + PG8_SA(b, h) + aoff + m * 2048 + k * 1024); } while (0)
; #define PG8_MMA(ai, bj, At, Bt) do { __builtin_amdgcn_s_setprio(1); _Pragma("unroll") for (int m = 0; m < 4; ++m) _Pragma("unroll") for (int n = 0; n < 2; ++n) _Pragma("unroll") for (int k = 0; k < 2; ++k) \
;         acc[ai][bj][m][n] = __builtin_amdgcn_mfma_f32_16x16x32_bf16(Bt[n][k], At[m][k], acc[ai][bj][m][n], 0, 0, 0); __builtin_amdgcn_s_setprio(0); } while (0)
; #define PG8_WAIT_V(n) asm volatile("s_waitcnt vmcnt(" #n ")" ::: "memory")
; #define PG8_WAIT_L(n) asm volatile("s_waitcnt lgkmcnt(" #n ")" ::: "memory")
; #define PG8_BAR __builtin_amdgcn_s_barrier()
; #define PG8_SCHED __builtin_amdgcn_sched_barrier(0)
; template <class Epi, class Sched, bool ALIGN_EPI = false, bool SP2 = false>
; __device__ __forceinline__ void gemm_phase(PG8_LAS unsigned char* lds, const Gemm g, const Sched& S, const Epi& E) {
;     ...
;             PG8_LDA(At, 1, 1); PG8_STAGE(PG8_SB(1, 0), b3, voffB); PG8_STAGE(PG8_SB(1, 1), b3 + hB, voffB); PG8_STAGE(PG8_SA(1, 0), a3, voffA);
;             PG8_WAIT_V(8); PG8_WAIT_L(0); PG8_BAR; PG8_MMA(1, 0, At, B0); PG8_MMA(1, 1, At, B1); PG8_BAR; PG8_SCHED;
;     ...
;         if constexpr (ALIGN_EPI) { if (wr == 0) PG8_BAR; }
	s_add_i32 s18, s18, s58
	v_lshl_add_u64 v[216:217], v[216:217], 0, s[16:17]
	s_mov_b32 m0, s18
	ds_read_b128 v[184:187], v174 offset:49152
	ds_read_b128 v[188:191], v174 offset:50176
	ds_read_b128 v[192:195], v174 offset:51200
	ds_read_b128 v[196:199], v174 offset:52224
	ds_read_b128 v[200:203], v174 offset:53248
	ds_read_b128 v[204:207], v174 offset:54272
	ds_read_b128 v[208:211], v174 offset:55296
	ds_read_b128 v[212:215], v174 offset:56320
	global_load_lds_dwordx4 v[216:217], off
	s_add_i32 m0, s18, 0x2000
	s_add_u32 s46, s46, 0x80080
	v_lshl_add_u64 v[216:217], v[218:219], 0, s[16:17]
	s_addc_u32 s47, s47, 0
	s_add_i32 s18, s19, s58
	global_load_lds_dwordx4 v[216:217], off
	v_lshl_add_u64 v[216:217], s[46:47], 0, v[150:151]
	s_mov_b32 m0, s18
	s_nop 0
	global_load_lds_dwordx4 v[216:217], off
	v_lshl_add_u64 v[216:217], s[46:47], 0, v[146:147]
	s_add_i32 m0, s18, 0x2000
	s_nop 0
	global_load_lds_dwordx4 v[216:217], off
	v_lshl_add_u64 v[216:217], v[220:221], 0, s[16:17]
	s_mov_b32 m0, s63
	s_nop 0
	global_load_lds_dwordx4 v[216:217], off
	v_lshl_add_u64 v[216:217], v[224:225], 0, s[16:17]
	s_mov_b32 m0, s64
	s_nop 0
	global_load_lds_dwordx4 v[216:217], off
	s_waitcnt vmcnt(8) lgkmcnt(0)
	s_barrier
	v_mfma_f32_16x16x32_bf16 v[62:65], v[130:133], v[184:187], v[62:65]
	v_mfma_f32_16x16x32_bf16 v[58:61], v[138:141], v[184:187], v[58:61]
	v_mfma_f32_16x16x32_bf16 v[46:49], v[130:133], v[192:195], v[46:49]
	v_mfma_f32_16x16x32_bf16 v[42:45], v[138:141], v[192:195], v[42:45]
	v_mfma_f32_16x16x32_bf16 v[30:33], v[130:133], v[200:203], v[30:33]
	v_mfma_f32_16x16x32_bf16 v[26:29], v[138:141], v[200:203], v[26:29]
	v_mfma_f32_16x16x32_bf16 v[14:17], v[130:133], v[208:211], v[14:17]
	v_mfma_f32_16x16x32_bf16 v[10:13], v[138:141], v[208:211], v[10:13]
	v_mfma_f32_16x16x32_bf16 v[62:65], v[134:137], v[188:191], v[62:65]
	v_mfma_f32_16x16x32_bf16 v[58:61], v[142:145], v[188:191], v[58:61]
	v_mfma_f32_16x16x32_bf16 v[46:49], v[134:137], v[196:199], v[46:49]
	v_mfma_f32_16x16x32_bf16 v[42:45], v[142:145], v[196:199], v[42:45]
	v_mfma_f32_16x16x32_bf16 v[30:33], v[134:137], v[204:207], v[30:33]
	v_mfma_f32_16x16x32_bf16 v[26:29], v[142:145], v[204:207], v[26:29]
	v_mfma_f32_16x16x32_bf16 v[14:17], v[134:137], v[212:215], v[14:17]
	v_mfma_f32_16x16x32_bf16 v[10:13], v[142:145], v[212:215], v[10:13]
	v_mfma_f32_16x16x32_bf16 v[54:57], v[162:165], v[184:187], v[54:57]
	v_mfma_f32_16x16x32_bf16 v[50:53], v[176:179], v[184:187], v[50:53]
	v_mfma_f32_16x16x32_bf16 v[38:41], v[162:165], v[192:195], v[38:41]
	v_mfma_f32_16x16x32_bf16 v[34:37], v[176:179], v[192:195], v[34:37]
	v_mfma_f32_16x16x32_bf16 v[22:25], v[162:165], v[200:203], v[22:25]
	v_mfma_f32_16x16x32_bf16 v[18:21], v[176:179], v[200:203], v[18:21]
	v_mfma_f32_16x16x32_bf16 v[6:9], v[162:165], v[208:211], v[6:9]
	v_mfma_f32_16x16x32_bf16 v[2:5], v[176:179], v[208:211], v[2:5]
	v_mfma_f32_16x16x32_bf16 v[54:57], v[166:169], v[188:191], v[54:57]
	v_mfma_f32_16x16x32_bf16 v[50:53], v[180:183], v[188:191], v[50:53]
	v_mfma_f32_16x16x32_bf16 v[38:41], v[166:169], v[196:199], v[38:41]
	v_mfma_f32_16x16x32_bf16 v[34:37], v[180:183], v[196:199], v[34:37]
	v_mfma_f32_16x16x32_bf16 v[22:25], v[166:169], v[204:207], v[22:25]
	v_mfma_f32_16x16x32_bf16 v[18:21], v[180:183], v[204:207], v[18:21]
	v_mfma_f32_16x16x32_bf16 v[6:9], v[166:169], v[212:215], v[6:9]
	v_mfma_f32_16x16x32_bf16 v[2:5], v[180:183], v[212:215], v[2:5]
	s_barrier
	s_add_i32 s74, s74, 2
	s_add_u32 s44, s44, 0x100
	s_addc_u32 s45, s45, 0
	s_add_u32 s72, s72, 0x100
	s_addc_u32 s73, s73, 0
	s_cmp_gt_u32 s74, 29
	s_cbranch_scc0 .LBB0_888
	s_and_b64 vcc, exec, s[20:21]
	s_cbranch_vccz .LBB0_891
	s_barrier

; #define PG8_STAGE(bufoff, gbase, voff) do { _Pragma("unroll") for (int _i = 0; _i < 2; ++_i) \
;         __builtin_amdgcn_global_load_lds((const unsigned*)((const char*)(gbase) + (voff)[_i]), (PG8_LAS unsigned*)(lds + (bufoff) + ldsw + _i * 8192), 16, 0, 0); } while (0)
; #define PG8_LDA(dst, b, h) do { _Pragma("unroll") for (int m = 0; m < 4; ++m) _Pragma("unroll") for (int k = 0; k < 2; ++k) dst[m][k] = *(const PG8_LAS bf16x8*)(lds + PG8_SA(b, h) + aoff + m * 2048 + k * 1024); } while (0)
; #define PG8_LDB(dst, b, h) do { _Pragma("unroll") for (int n = 0; n < 2; ++n) _Pragma("unroll") for (int k = 0; k < 2; ++k) dst[n][k] = *(const PG8_LAS bf16x8*)(lds + PG8_SB(b, h) + boff + n * 2048 + k * 1024); } while (0)
; #define PG8_MMA(ai, bj, At, Bt) do { __builtin_amdgcn_s_setprio(1); _Pragma("unroll") for (int m = 0; m < 4; ++m) _Pragma("unroll") for (int n = 0; n < 2; ++n) _Pragma("unroll") for (int k = 0; k < 2; ++k) \
;         acc[ai][bj][m][n] = __builtin_amdgcn_mfma_f32_16x16x32_bf16(Bt[n][k], At[m][k], acc[ai][bj][m][n], 0, 0, 0); __builtin_amdgcn_s_setprio(0); } while (0)
; #define PG8_WAIT_V(n) asm volatile("s_waitcnt vmcnt(" #n ")" ::: "memory")
; #define PG8_WAIT_L(n) asm volatile("s_waitcnt lgkmcnt(" #n ")" ::: "memory")
; template <class Epi, class Sched, bool ALIGN_EPI = false, bool SP2 = false>
; __device__ __forceinline__ void gemm_phase(PG8_LAS unsigned char* lds, const Gemm g, const Sched& S, const Epi& E) {
;     ...
;             const bool last = (t == nt - 2);
;             const char* a1 = cA + (size_t)(t + 1) * kstep;
;             const char* a2 = last ? nA : cA + (size_t)(t + 2) * kstep; const char* b2 = last ? nB : cB + (size_t)(t + 2) * kstep;
;             const char* a3 = a2 + kstep; const char* b3 = b2 + kstep;
;             if (last && has_next) S.a_ready(nxt);
;             if constexpr (SP2) {
;             PG8_LDB(B0, 0, 0); PG8_LDB(B1, 0, 1); PG8_SCHED; PG8_LDA(At, 0, 0); PG8_STAGE(PG8_SA(1, 1), a1 + hA, voffA);
;             PG8_WAIT_V(8); PG8_WAIT_L(0); PG8_BAR; PG8_MMA(0, 0, At, B0); PG8_MMA(0, 1, At, B1); PG8_BAR; PG8_SCHED;
;             PG8_LDA(At, 0, 1); PG8_STAGE(PG8_SB(0, 0), b2, voffB); PG8_STAGE(PG8_SB(0, 1), b2 + hB, voffB); PG8_STAGE(PG8_SA(0, 0), a2, voffA);
;             PG8_WAIT_V(8); PG8_WAIT_L(0); PG8_BAR; PG8_MMA(1, 0, At, B0); PG8_MMA(1, 1, At, B1); PG8_BAR; PG8_SCHED;
.LBB0_963:
	ds_read_b128 v[130:133], v208
	ds_read_b128 v[134:137], v208 offset:1024
	ds_read_b128 v[138:141], v208 offset:2048
	ds_read_b128 v[142:145], v208 offset:3072
	ds_read_b128 v[146:149], v209
	ds_read_b128 v[150:153], v209 offset:1024
	ds_read_b128 v[154:157], v209 offset:2048
	ds_read_b128 v[158:161], v209 offset:3072
	s_add_u32 s18, s48, 0xfff80080
	s_addc_u32 s19, s49, -1
	s_cmp_eq_u32 s78, 28
	s_cselect_b32 s53, s41, s19
	s_cselect_b32 s52, s47, s18
	s_cselect_b32 s51, s39, s77
	s_cselect_b32 s50, s75, s76
	v_lshl_add_u64 v[216:217], s[48:49], 0, v[186:187]
	s_add_i32 m0, s62, 0xc000
	ds_read_b128 v[162:165], v210
	ds_read_b128 v[166:169], v210 offset:1024
	ds_read_b128 v[170:173], v210 offset:2048
	ds_read_b128 v[174:177], v210 offset:3072
	ds_read_b128 v[194:197], v210 offset:4096
	ds_read_b128 v[198:201], v210 offset:5120
	ds_read_b128 v[202:205], v210 offset:6144
	ds_read_b128 v[212:215], v210 offset:7168
	global_load_lds_dwordx4 v[216:217], off
	v_lshl_add_u64 v[216:217], s[48:49], 0, v[188:189]
	s_add_i32 m0, s62, 0xe000
	s_nop 0
	global_load_lds_dwordx4 v[216:217], off
	s_waitcnt vmcnt(8) lgkmcnt(0)
	s_barrier
	v_mfma_f32_16x16x32_bf16 v[126:129], v[130:133], v[162:165], v[126:129]
	v_mfma_f32_16x16x32_bf16 v[122:125], v[138:141], v[162:165], v[122:125]
	v_mfma_f32_16x16x32_bf16 v[110:113], v[130:133], v[170:173], v[110:113]
	v_mfma_f32_16x16x32_bf16 v[106:109], v[138:141], v[170:173], v[106:109]
	v_mfma_f32_16x16x32_bf16 v[94:97], v[130:133], v[194:197], v[94:97]
	v_mfma_f32_16x16x32_bf16 v[90:93], v[138:141], v[194:197], v[90:93]
	v_mfma_f32_16x16x32_bf16 v[78:81], v[130:133], v[202:205], v[78:81]
	v_mfma_f32_16x16x32_bf16 v[74:77], v[138:141], v[202:205], v[74:77]
	v_mfma_f32_16x16x32_bf16 v[126:129], v[134:137], v[166:169], v[126:129]
	v_mfma_f32_16x16x32_bf16 v[122:125], v[142:145], v[166:169], v[122:125]
	v_mfma_f32_16x16x32_bf16 v[110:113], v[134:137], v[174:177], v[110:113]
	v_mfma_f32_16x16x32_bf16 v[106:109], v[142:145], v[174:177], v[106:109]
	v_mfma_f32_16x16x32_bf16 v[94:97], v[134:137], v[198:201], v[94:97]
	v_mfma_f32_16x16x32_bf16 v[90:93], v[142:145], v[198:201], v[90:93]
	v_mfma_f32_16x16x32_bf16 v[78:81], v[134:137], v[212:215], v[78:81]
	v_mfma_f32_16x16x32_bf16 v[74:77], v[142:145], v[212:215], v[74:77]
	v_mfma_f32_16x16x32_bf16 v[118:121], v[146:149], v[162:165], v[118:121]
	v_mfma_f32_16x16x32_bf16 v[114:117], v[154:157], v[162:165], v[114:117]
	v_mfma_f32_16x16x32_bf16 v[102:105], v[146:149], v[170:173], v[102:105]
	v_mfma_f32_16x16x32_bf16 v[98:101], v[154:157], v[170:173], v[98:101]
	v_mfma_f32_16x16x32_bf16 v[86:89], v[146:149], v[194:197], v[86:89]
	v_mfma_f32_16x16x32_bf16 v[82:85], v[154:157], v[194:197], v[82:85]
	v_mfma_f32_16x16x32_bf16 v[70:73], v[146:149], v[202:205], v[70:73]
	v_mfma_f32_16x16x32_bf16 v[66:69], v[154:157], v[202:205], v[66:69]
	v_mfma_f32_16x16x32_bf16 v[118:121], v[150:153], v[166:169], v[118:121]
	v_mfma_f32_16x16x32_bf16 v[114:117], v[158:161], v[166:169], v[114:117]
	v_mfma_f32_16x16x32_bf16 v[102:105], v[150:153], v[174:177], v[102:105]
	v_mfma_f32_16x16x32_bf16 v[98:101], v[158:161], v[174:177], v[98:101]
	v_mfma_f32_16x16x32_bf16 v[86:89], v[150:153], v[198:201], v[86:89]
	v_mfma_f32_16x16x32_bf16 v[82:85], v[158:161], v[198:201], v[82:85]
	v_mfma_f32_16x16x32_bf16 v[70:73], v[150:153], v[212:215], v[70:73]
	v_mfma_f32_16x16x32_bf16 v[66:69], v[158:161], v[212:215], v[66:69]
	s_barrier
	s_add_i32 s18, s72, s61
	v_lshl_add_u64 v[216:217], s[50:51], 0, v[180:181]
	s_mov_b32 m0, s18
	ds_read_b128 v[162:165], v210 offset:16384
	ds_read_b128 v[166:169], v210 offset:17408
	ds_read_b128 v[170:173], v210 offset:18432
	ds_read_b128 v[174:177], v210 offset:19456
	ds_read_b128 v[194:197], v210 offset:20480
	ds_read_b128 v[198:201], v210 offset:21504
	ds_read_b128 v[202:205], v210 offset:22528
	ds_read_b128 v[212:215], v210 offset:23552
	global_load_lds_dwordx4 v[216:217], off
	s_add_i32 m0, s18, 0x2000
	s_add_u32 s80, s50, 0x80000
	v_lshl_add_u64 v[218:219], s[50:51], 0, v[184:185]
	s_addc_u32 s81, s51, 0
	s_add_i32 s18, s73, s61
	global_load_lds_dwordx4 v[218:219], off
	v_lshl_add_u64 v[220:221], s[80:81], 0, v[180:181]
	s_mov_b32 m0, s18
	v_lshl_add_u64 v[224:225], s[52:53], 0, v[182:183]
	global_load_lds_dwordx4 v[220:221], off
	v_lshl_add_u64 v[220:221], s[80:81], 0, v[184:185]
	s_add_i32 m0, s18, 0x2000
	s_nop 0
	global_load_lds_dwordx4 v[220:221], off
	v_lshl_add_u64 v[220:221], s[52:53], 0, v[178:179]
	s_mov_b32 m0, s62
	s_nop 0
	global_load_lds_dwordx4 v[220:221], off
	s_mov_b32 m0, s63
	s_nop 0
	global_load_lds_dwordx4 v[224:225], off
	s_waitcnt vmcnt(8) lgkmcnt(0)
	s_barrier
; #define PG8_STAGE(bufoff, gbase, voff) do { _Pragma("unroll") for (int _i = 0; _i < 2; ++_i) \
;         __builtin_amdgcn_global_load_lds((const unsigned*)((const char*)(gbase) + (voff)[_i]), (PG8_LAS unsigned*)(lds + (bufoff) + ldsw + _i * 8192), 16, 0, 0); } while (0)
; #define PG8_LDA(dst, b, h) do { _Pragma("unroll") for (int m = 0; m < 4; ++m) _Pragma("unroll") for (int k = 0; k < 2; ++k) dst[m][k] = *(const PG8_LAS bf16x8*)(lds + PG8_SA(b, h) + aoff + m * 2048 + k * 1024); } while (0)
; #define PG8_LDB(dst, b, h) do { _Pragma("unroll") for (int n = 0; n < 2; ++n) _Pragma("unroll") for (int k = 0; k < 2; ++k) dst[n][k] = *(const PG8_LAS bf16x8*)(lds + PG8_SB(b, h) + boff + n * 2048 + k * 1024); } while (0)
; #define PG8_MMA(ai, bj, At, Bt) do { __builtin_amdgcn_s_setprio(1); _Pragma("unroll") for (int m = 0; m < 4; ++m) _Pragma("unroll") for (int n = 0; n < 2; ++n) _Pragma("unroll") for (int k = 0; k < 2; ++k) \
;         acc[ai][bj][m][n] = __builtin_amdgcn_mfma_f32_16x16x32_bf16(Bt[n][k], At[m][k], acc[ai][bj][m][n], 0, 0, 0); __builtin_amdgcn_s_setprio(0); } while (0)
; #define PG8_WAIT_V(n) asm volatile("s_waitcnt vmcnt(" #n ")" ::: "memory")
; #define PG8_WAIT_L(n) asm volatile("s_waitcnt lgkmcnt(" #n ")" ::: "memory")
; #define PG8_BAR __builtin_amdgcn_s_barrier()
; #define PG8_SCHED __builtin_amdgcn_sched_barrier(0)
; template <class Epi, class Sched, bool ALIGN_EPI = false, bool SP2 = false>
; __device__ __forceinline__ void gemm_phase(PG8_LAS unsigned char* lds, const Gemm g, const Sched& S, const Epi& E) {
;     ...
;             PG8_WAIT_V(8); PG8_WAIT_L(0); PG8_BAR; PG8_MMA(1, 0, At, B0); PG8_MMA(1, 1, At, B1); PG8_BAR; PG8_SCHED;
;             PG8_LDB(B0, 1, 0); PG8_LDB(B1, 1, 1); PG8_SCHED; PG8_LDA(At, 1, 0); PG8_STAGE(PG8_SA(0, 1), a2 + hA, voffA);
;             PG8_WAIT_V(8); PG8_WAIT_L(0); PG8_BAR; PG8_MMA(0, 0, At, B0); PG8_MMA(0, 1, At, B1); PG8_BAR; PG8_SCHED;
	v_mfma_f32_16x16x32_bf16 v[62:65], v[130:133], v[162:165], v[62:65]
	v_mfma_f32_16x16x32_bf16 v[58:61], v[138:141], v[162:165], v[58:61]
	v_mfma_f32_16x16x32_bf16 v[46:49], v[130:133], v[170:173], v[46:49]
	v_mfma_f32_16x16x32_bf16 v[42:45], v[138:141], v[170:173], v[42:45]
	v_mfma_f32_16x16x32_bf16 v[30:33], v[130:133], v[194:197], v[30:33]
	v_mfma_f32_16x16x32_bf16 v[26:29], v[138:141], v[194:197], v[26:29]
	v_mfma_f32_16x16x32_bf16 v[14:17], v[130:133], v[202:205], v[14:17]
	v_mfma_f32_16x16x32_bf16 v[10:13], v[138:141], v[202:205], v[10:13]
	v_mfma_f32_16x16x32_bf16 v[62:65], v[134:137], v[166:169], v[62:65]
	v_mfma_f32_16x16x32_bf16 v[58:61], v[142:145], v[166:169], v[58:61]
	v_mfma_f32_16x16x32_bf16 v[46:49], v[134:137], v[174:177], v[46:49]
	v_mfma_f32_16x16x32_bf16 v[42:45], v[142:145], v[174:177], v[42:45]
	v_mfma_f32_16x16x32_bf16 v[30:33], v[134:137], v[198:201], v[30:33]
	v_mfma_f32_16x16x32_bf16 v[26:29], v[142:145], v[198:201], v[26:29]
	v_mfma_f32_16x16x32_bf16 v[14:17], v[134:137], v[212:215], v[14:17]
	v_mfma_f32_16x16x32_bf16 v[10:13], v[142:145], v[212:215], v[10:13]
	v_mfma_f32_16x16x32_bf16 v[54:57], v[146:149], v[162:165], v[54:57]
	v_mfma_f32_16x16x32_bf16 v[50:53], v[154:157], v[162:165], v[50:53]
	v_mfma_f32_16x16x32_bf16 v[38:41], v[146:149], v[170:173], v[38:41]
	v_mfma_f32_16x16x32_bf16 v[34:37], v[154:157], v[170:173], v[34:37]
	v_mfma_f32_16x16x32_bf16 v[22:25], v[146:149], v[194:197], v[22:25]
	v_mfma_f32_16x16x32_bf16 v[18:21], v[154:157], v[194:197], v[18:21]
	v_mfma_f32_16x16x32_bf16 v[6:9], v[146:149], v[202:205], v[6:9]
	v_mfma_f32_16x16x32_bf16 v[2:5], v[154:157], v[202:205], v[2:5]
	v_mfma_f32_16x16x32_bf16 v[54:57], v[150:153], v[166:169], v[54:57]
	v_mfma_f32_16x16x32_bf16 v[50:53], v[158:161], v[166:169], v[50:53]
	v_mfma_f32_16x16x32_bf16 v[38:41], v[150:153], v[174:177], v[38:41]
	v_mfma_f32_16x16x32_bf16 v[34:37], v[158:161], v[174:177], v[34:37]
	v_mfma_f32_16x16x32_bf16 v[22:25], v[150:153], v[198:201], v[22:25]
	v_mfma_f32_16x16x32_bf16 v[18:21], v[158:161], v[198:201], v[18:21]
	v_mfma_f32_16x16x32_bf16 v[6:9], v[150:153], v[212:215], v[6:9]
	v_mfma_f32_16x16x32_bf16 v[2:5], v[158:161], v[212:215], v[2:5]
	s_barrier
	s_add_i32 s18, 0, 0x18000
	s_add_i32 s19, 0, 0x1c000
	v_add_u32_e32 v142, s18, v206
	v_add_u32_e32 v158, s19, v206
	ds_read_b128 v[130:133], v142
	ds_read_b128 v[134:137], v142 offset:1024
	ds_read_b128 v[138:141], v142 offset:2048
	ds_read_b128 v[142:145], v142 offset:3072
	ds_read_b128 v[146:149], v158
	ds_read_b128 v[150:153], v158 offset:1024
	ds_read_b128 v[154:157], v158 offset:2048
	ds_read_b128 v[158:161], v158 offset:3072
	s_add_u32 s52, s52, 0x80000
	s_addc_u32 s53, s53, 0
	s_mov_b32 m0, s64
	v_lshl_add_u64 v[226:227], s[52:53], 0, v[178:179]
	ds_read_b128 v[162:165], v210 offset:32768
	ds_read_b128 v[166:169], v210 offset:33792
	ds_read_b128 v[170:173], v210 offset:34816
	ds_read_b128 v[174:177], v210 offset:35840
	ds_read_b128 v[194:197], v210 offset:36864
	ds_read_b128 v[198:201], v210 offset:37888
	ds_read_b128 v[202:205], v210 offset:38912
	ds_read_b128 v[212:215], v210 offset:39936
	global_load_lds_dwordx4 v[226:227], off
	v_lshl_add_u64 v[226:227], s[52:53], 0, v[182:183]
	s_mov_b32 m0, s65
	s_nop 0
	global_load_lds_dwordx4 v[226:227], off
	s_waitcnt vmcnt(8) lgkmcnt(0)
	s_barrier
	v_mfma_f32_16x16x32_bf16 v[126:129], v[130:133], v[162:165], v[126:129]
	v_mfma_f32_16x16x32_bf16 v[122:125], v[138:141], v[162:165], v[122:125]
	v_mfma_f32_16x16x32_bf16 v[110:113], v[130:133], v[170:173], v[110:113]
	v_mfma_f32_16x16x32_bf16 v[106:109], v[138:141], v[170:173], v[106:109]
	v_mfma_f32_16x16x32_bf16 v[94:97], v[130:133], v[194:197], v[94:97]
	v_mfma_f32_16x16x32_bf16 v[90:93], v[138:141], v[194:197], v[90:93]
	v_mfma_f32_16x16x32_bf16 v[78:81], v[130:133], v[202:205], v[78:81]
	v_mfma_f32_16x16x32_bf16 v[74:77], v[138:141], v[202:205], v[74:77]
	v_mfma_f32_16x16x32_bf16 v[126:129], v[134:137], v[166:169], v[126:129]
	v_mfma_f32_16x16x32_bf16 v[122:125], v[142:145], v[166:169], v[122:125]
	v_mfma_f32_16x16x32_bf16 v[110:113], v[134:137], v[174:177], v[110:113]
	v_mfma_f32_16x16x32_bf16 v[106:109], v[142:145], v[174:177], v[106:109]
	v_mfma_f32_16x16x32_bf16 v[94:97], v[134:137], v[198:201], v[94:97]
	v_mfma_f32_16x16x32_bf16 v[90:93], v[142:145], v[198:201], v[90:93]
	v_mfma_f32_16x16x32_bf16 v[78:81], v[134:137], v[212:215], v[78:81]
	v_mfma_f32_16x16x32_bf16 v[74:77], v[142:145], v[212:215], v[74:77]
	v_mfma_f32_16x16x32_bf16 v[118:121], v[146:149], v[162:165], v[118:121]
	v_mfma_f32_16x16x32_bf16 v[114:117], v[154:157], v[162:165], v[114:117]
	v_mfma_f32_16x16x32_bf16 v[102:105], v[146:149], v[170:173], v[102:105]
	v_mfma_f32_16x16x32_bf16 v[98:101], v[154:157], v[170:173], v[98:101]
	v_mfma_f32_16x16x32_bf16 v[86:89], v[146:149], v[194:197], v[86:89]
	v_mfma_f32_16x16x32_bf16 v[82:85], v[154:157], v[194:197], v[82:85]
	v_mfma_f32_16x16x32_bf16 v[70:73], v[146:149], v[202:205], v[70:73]
	v_mfma_f32_16x16x32_bf16 v[66:69], v[154:157], v[202:205], v[66:69]
	v_mfma_f32_16x16x32_bf16 v[118:121], v[150:153], v[166:169], v[118:121]
	v_mfma_f32_16x16x32_bf16 v[114:117], v[158:161], v[166:169], v[114:117]
	v_mfma_f32_16x16x32_bf16 v[102:105], v[150:153], v[174:177], v[102:105]
	v_mfma_f32_16x16x32_bf16 v[98:101], v[158:161], v[174:177], v[98:101]
	v_mfma_f32_16x16x32_bf16 v[86:89], v[150:153], v[198:201], v[86:89]
	v_mfma_f32_16x16x32_bf16 v[82:85], v[158:161], v[198:201], v[82:85]
	v_mfma_f32_16x16x32_bf16 v[70:73], v[150:153], v[212:215], v[70:73]
	v_mfma_f32_16x16x32_bf16 v[66:69], v[158:161], v[212:215], v[66:69]
	s_barrier
; #define PG8_STAGE(bufoff, gbase, voff) do { _Pragma("unroll") for (int _i = 0; _i < 2; ++_i) \
;         __builtin_amdgcn_global_load_lds((const unsigned*)((const char*)(gbase) + (voff)[_i]), (PG8_LAS unsigned*)(lds + (bufoff) + ldsw + _i * 8192), 16, 0, 0); } while (0)
; #define PG8_LDA(dst, b, h) do { _Pragma("unroll") for (int m = 0; m < 4; ++m) _Pragma("unroll") for (int k = 0; k < 2; ++k) dst[m][k] = *(const PG8_LAS bf16x8*)(lds + PG8_SA(b, h) + aoff + m * 2048 + k * 1024); } while (0)
; #define PG8_MMA(ai, bj, At, Bt) do { __builtin_amdgcn_s_setprio(1); _Pragma("unroll") for (int m = 0; m < 4; ++m) _Pragma("unroll") for (int n = 0; n < 2; ++n) _Pragma("unroll") for (int k = 0; k < 2; ++k) \
;         acc[ai][bj][m][n] = __builtin_amdgcn_mfma_f32_16x16x32_bf16(Bt[n][k], At[m][k], acc[ai][bj][m][n], 0, 0, 0); __builtin_amdgcn_s_setprio(0); } while (0)
; #define PG8_WAIT_V(n) asm volatile("s_waitcnt vmcnt(" #n ")" ::: "memory")
; #define PG8_WAIT_L(n) asm volatile("s_waitcnt lgkmcnt(" #n ")" ::: "memory")
; #define PG8_BAR __builtin_amdgcn_s_barrier()
; #define PG8_SCHED __builtin_amdgcn_sched_barrier(0)
; template <class Epi, class Sched, bool ALIGN_EPI = false, bool SP2 = false>
; __device__ __forceinline__ void gemm_phase(PG8_LAS unsigned char* lds, const Gemm g, const Sched& S, const Epi& E) {
;     ...
;             PG8_LDA(At, 1, 1); PG8_STAGE(PG8_SB(1, 0), b3, voffB); PG8_STAGE(PG8_SB(1, 1), b3 + hB, voffB); PG8_STAGE(PG8_SA(1, 0), a3, voffA);
;             PG8_WAIT_V(8); PG8_WAIT_L(0); PG8_BAR; PG8_MMA(1, 0, At, B0); PG8_MMA(1, 1, At, B1); PG8_BAR; PG8_SCHED;
;     ...
;         if constexpr (ALIGN_EPI) { if (wr == 0) PG8_BAR; }
	s_add_i32 s18, s18, s61
	v_lshl_add_u64 v[216:217], v[216:217], 0, s[22:23]
	s_mov_b32 m0, s18
	ds_read_b128 v[162:165], v210 offset:49152
	ds_read_b128 v[166:169], v210 offset:50176
	ds_read_b128 v[170:173], v210 offset:51200
	ds_read_b128 v[174:177], v210 offset:52224
	ds_read_b128 v[194:197], v210 offset:53248
	ds_read_b128 v[198:201], v210 offset:54272
	ds_read_b128 v[202:205], v210 offset:55296
	ds_read_b128 v[212:215], v210 offset:56320
	global_load_lds_dwordx4 v[216:217], off
	s_add_i32 m0, s18, 0x2000
	s_add_u32 s50, s50, 0x80080
	v_lshl_add_u64 v[216:217], v[218:219], 0, s[22:23]
	s_addc_u32 s51, s51, 0
	s_add_i32 s18, s19, s61
	global_load_lds_dwordx4 v[216:217], off
	v_lshl_add_u64 v[216:217], s[50:51], 0, v[180:181]
	s_mov_b32 m0, s18
	s_nop 0
	global_load_lds_dwordx4 v[216:217], off
	v_lshl_add_u64 v[216:217], s[50:51], 0, v[184:185]
	s_add_i32 m0, s18, 0x2000
	s_nop 0
	global_load_lds_dwordx4 v[216:217], off
	v_lshl_add_u64 v[216:217], v[220:221], 0, s[22:23]
	s_mov_b32 m0, s69
	s_nop 0
	global_load_lds_dwordx4 v[216:217], off
	v_lshl_add_u64 v[216:217], v[224:225], 0, s[22:23]
	s_mov_b32 m0, s70
	s_nop 0
	global_load_lds_dwordx4 v[216:217], off
	s_waitcnt vmcnt(8) lgkmcnt(0)
	s_barrier
	v_mfma_f32_16x16x32_bf16 v[62:65], v[130:133], v[162:165], v[62:65]
	v_mfma_f32_16x16x32_bf16 v[58:61], v[138:141], v[162:165], v[58:61]
	v_mfma_f32_16x16x32_bf16 v[46:49], v[130:133], v[170:173], v[46:49]
	v_mfma_f32_16x16x32_bf16 v[42:45], v[138:141], v[170:173], v[42:45]
	v_mfma_f32_16x16x32_bf16 v[30:33], v[130:133], v[194:197], v[30:33]
	v_mfma_f32_16x16x32_bf16 v[26:29], v[138:141], v[194:197], v[26:29]
	v_mfma_f32_16x16x32_bf16 v[14:17], v[130:133], v[202:205], v[14:17]
	v_mfma_f32_16x16x32_bf16 v[10:13], v[138:141], v[202:205], v[10:13]
	v_mfma_f32_16x16x32_bf16 v[62:65], v[134:137], v[166:169], v[62:65]
	v_mfma_f32_16x16x32_bf16 v[58:61], v[142:145], v[166:169], v[58:61]
	v_mfma_f32_16x16x32_bf16 v[46:49], v[134:137], v[174:177], v[46:49]
	v_mfma_f32_16x16x32_bf16 v[42:45], v[142:145], v[174:177], v[42:45]
	v_mfma_f32_16x16x32_bf16 v[30:33], v[134:137], v[198:201], v[30:33]
	v_mfma_f32_16x16x32_bf16 v[26:29], v[142:145], v[198:201], v[26:29]
	v_mfma_f32_16x16x32_bf16 v[14:17], v[134:137], v[212:215], v[14:17]
	v_mfma_f32_16x16x32_bf16 v[10:13], v[142:145], v[212:215], v[10:13]
	v_mfma_f32_16x16x32_bf16 v[54:57], v[146:149], v[162:165], v[54:57]
	v_mfma_f32_16x16x32_bf16 v[50:53], v[154:157], v[162:165], v[50:53]
	v_mfma_f32_16x16x32_bf16 v[38:41], v[146:149], v[170:173], v[38:41]
	v_mfma_f32_16x16x32_bf16 v[34:37], v[154:157], v[170:173], v[34:37]
	v_mfma_f32_16x16x32_bf16 v[22:25], v[146:149], v[194:197], v[22:25]
	v_mfma_f32_16x16x32_bf16 v[18:21], v[154:157], v[194:197], v[18:21]
	v_mfma_f32_16x16x32_bf16 v[6:9], v[146:149], v[202:205], v[6:9]
	v_mfma_f32_16x16x32_bf16 v[2:5], v[154:157], v[202:205], v[2:5]
	v_mfma_f32_16x16x32_bf16 v[54:57], v[150:153], v[166:169], v[54:57]
	v_mfma_f32_16x16x32_bf16 v[50:53], v[158:161], v[166:169], v[50:53]
	v_mfma_f32_16x16x32_bf16 v[38:41], v[150:153], v[174:177], v[38:41]
	v_mfma_f32_16x16x32_bf16 v[34:37], v[158:161], v[174:177], v[34:37]
	v_mfma_f32_16x16x32_bf16 v[22:25], v[150:153], v[198:201], v[22:25]
	v_mfma_f32_16x16x32_bf16 v[18:21], v[158:161], v[198:201], v[18:21]
	v_mfma_f32_16x16x32_bf16 v[6:9], v[150:153], v[212:215], v[6:9]
	v_mfma_f32_16x16x32_bf16 v[2:5], v[158:161], v[212:215], v[2:5]
	s_barrier
	s_add_i32 s78, s78, 2
	s_add_u32 s48, s48, 0x100
	s_addc_u32 s49, s49, 0
	s_add_u32 s76, s76, 0x100
	s_addc_u32 s77, s77, 0
	s_cmp_gt_u32 s78, 29
	s_cbranch_scc0 .LBB0_963
	s_and_b64 vcc, exec, s[24:25]
	s_cbranch_vccz .LBB0_966
	s_barrier

; #define PG8_STAGE(bufoff, gbase, voff) do { _Pragma("unroll") for (int _i = 0; _i < 2; ++_i) \
;         __builtin_amdgcn_global_load_lds((const unsigned*)((const char*)(gbase) + (voff)[_i]), (PG8_LAS unsigned*)(lds + (bufoff) + ldsw + _i * 8192), 16, 0, 0); } while (0)
; #define PG8_LDA(dst, b, h) do { _Pragma("unroll") for (int m = 0; m < 4; ++m) _Pragma("unroll") for (int k = 0; k < 2; ++k) dst[m][k] = *(const PG8_LAS bf16x8*)(lds + PG8_SA(b, h) + aoff + m * 2048 + k * 1024); } while (0)
; #define PG8_LDB(dst, b, h) do { _Pragma("unroll") for (int n = 0; n < 2; ++n) _Pragma("unroll") for (int k = 0; k < 2; ++k) dst[n][k] = *(const PG8_LAS bf16x8*)(lds + PG8_SB(b, h) + boff + n * 2048 + k * 1024); } while (0)
; #define PG8_MMA(ai, bj, At, Bt) do { __builtin_amdgcn_s_setprio(1); _Pragma("unroll") for (int m = 0; m < 4; ++m) _Pragma("unroll") for (int n = 0; n < 2; ++n) _Pragma("unroll") for (int k = 0; k < 2; ++k) \
;         acc[ai][bj][m][n] = __builtin_amdgcn_mfma_f32_16x16x32_bf16(Bt[n][k], At[m][k], acc[ai][bj][m][n], 0, 0, 0); __builtin_amdgcn_s_setprio(0); } while (0)
; #define PG8_WAIT_V(n) asm volatile("s_waitcnt vmcnt(" #n ")" ::: "memory")
; #define PG8_WAIT_L(n) asm volatile("s_waitcnt lgkmcnt(" #n ")" ::: "memory")
; template <class Epi, class Sched, bool ALIGN_EPI = false, bool SP2 = false>
; __device__ __forceinline__ void gemm_phase(PG8_LAS unsigned char* lds, const Gemm g, const Sched& S, const Epi& E) {
;     ...
;             const bool last = (t == nt - 2);
;             const char* a1 = cA + (size_t)(t + 1) * kstep;
;             const char* a2 = last ? nA : cA + (size_t)(t + 2) * kstep; const char* b2 = last ? nB : cB + (size_t)(t + 2) * kstep;
;             const char* a3 = a2 + kstep; const char* b3 = b2 + kstep;
;             if (last && has_next) S.a_ready(nxt);
;             if constexpr (SP2) {
;             PG8_LDB(B0, 0, 0); PG8_LDB(B1, 0, 1); PG8_SCHED; PG8_LDA(At, 0, 0); PG8_STAGE(PG8_SA(1, 1), a1 + hA, voffA);
;             PG8_WAIT_V(8); PG8_WAIT_L(0); PG8_BAR; PG8_MMA(0, 0, At, B0); PG8_MMA(0, 1, At, B1); PG8_BAR; PG8_SCHED;
;             PG8_LDA(At, 0, 1); PG8_STAGE(PG8_SB(0, 0), b2, voffB); PG8_STAGE(PG8_SB(0, 1), b2 + hB, voffB); PG8_STAGE(PG8_SA(0, 0), a2, voffA);
;             PG8_WAIT_V(8); PG8_WAIT_L(0); PG8_BAR; PG8_MMA(1, 0, At, B0); PG8_MMA(1, 1, At, B1); PG8_BAR; PG8_SCHED;
.LBB0_1048:
	ds_read_b128 v[148:151], v169
	ds_read_b128 v[152:155], v169 offset:1024
	ds_read_b128 v[156:159], v169 offset:2048
	ds_read_b128 v[160:163], v169 offset:3072
	ds_read_b128 v[180:183], v171
	ds_read_b128 v[184:187], v171 offset:1024
	ds_read_b128 v[188:191], v171 offset:2048
	ds_read_b128 v[192:195], v171 offset:3072
	s_add_u32 s18, s8, 0xfff80080
	s_addc_u32 s19, s9, -1
	s_cmp_eq_u32 s72, 28
	s_cselect_b32 s45, s1, s19
	s_cselect_b32 s44, s37, s18
	s_cselect_b32 s43, s25, s71
	s_cselect_b32 s42, s69, s70
	v_lshl_add_u64 v[220:221], s[8:9], 0, v[140:141]
	s_add_i32 m0, s51, 0xc000
	ds_read_b128 v[196:199], v173
	ds_read_b128 v[200:203], v173 offset:1024
	ds_read_b128 v[204:207], v173 offset:2048
	ds_read_b128 v[208:211], v173 offset:3072
	ds_read_b128 v[212:215], v173 offset:4096
	ds_read_b128 v[216:219], v173 offset:5120
	ds_read_b128 v[224:227], v173 offset:6144
	ds_read_b128 v[228:231], v173 offset:7168
	global_load_lds_dwordx4 v[220:221], off
	v_lshl_add_u64 v[220:221], s[8:9], 0, v[142:143]
	s_add_i32 m0, s51, 0xe000
	s_nop 0
	global_load_lds_dwordx4 v[220:221], off
	s_waitcnt vmcnt(8) lgkmcnt(0)
	s_barrier
	v_mfma_f32_16x16x32_bf16 v[126:129], v[148:151], v[196:199], v[126:129]
	v_mfma_f32_16x16x32_bf16 v[122:125], v[156:159], v[196:199], v[122:125]
	v_mfma_f32_16x16x32_bf16 v[110:113], v[148:151], v[204:207], v[110:113]
	v_mfma_f32_16x16x32_bf16 v[106:109], v[156:159], v[204:207], v[106:109]
	v_mfma_f32_16x16x32_bf16 v[94:97], v[148:151], v[212:215], v[94:97]
	v_mfma_f32_16x16x32_bf16 v[90:93], v[156:159], v[212:215], v[90:93]
	v_mfma_f32_16x16x32_bf16 v[78:81], v[148:151], v[224:227], v[78:81]
	v_mfma_f32_16x16x32_bf16 v[74:77], v[156:159], v[224:227], v[74:77]
	v_mfma_f32_16x16x32_bf16 v[126:129], v[152:155], v[200:203], v[126:129]
	v_mfma_f32_16x16x32_bf16 v[122:125], v[160:163], v[200:203], v[122:125]
	v_mfma_f32_16x16x32_bf16 v[110:113], v[152:155], v[208:211], v[110:113]
	v_mfma_f32_16x16x32_bf16 v[106:109], v[160:163], v[208:211], v[106:109]
	v_mfma_f32_16x16x32_bf16 v[94:97], v[152:155], v[216:219], v[94:97]
	v_mfma_f32_16x16x32_bf16 v[90:93], v[160:163], v[216:219], v[90:93]
	v_mfma_f32_16x16x32_bf16 v[78:81], v[152:155], v[228:231], v[78:81]
	v_mfma_f32_16x16x32_bf16 v[74:77], v[160:163], v[228:231], v[74:77]
	v_mfma_f32_16x16x32_bf16 v[118:121], v[180:183], v[196:199], v[118:121]
	v_mfma_f32_16x16x32_bf16 v[114:117], v[188:191], v[196:199], v[114:117]
	v_mfma_f32_16x16x32_bf16 v[102:105], v[180:183], v[204:207], v[102:105]
	v_mfma_f32_16x16x32_bf16 v[98:101], v[188:191], v[204:207], v[98:101]
	v_mfma_f32_16x16x32_bf16 v[86:89], v[180:183], v[212:215], v[86:89]
	v_mfma_f32_16x16x32_bf16 v[82:85], v[188:191], v[212:215], v[82:85]
	v_mfma_f32_16x16x32_bf16 v[70:73], v[180:183], v[224:227], v[70:73]
	v_mfma_f32_16x16x32_bf16 v[66:69], v[188:191], v[224:227], v[66:69]
	v_mfma_f32_16x16x32_bf16 v[118:121], v[184:187], v[200:203], v[118:121]
	v_mfma_f32_16x16x32_bf16 v[114:117], v[192:195], v[200:203], v[114:117]
	v_mfma_f32_16x16x32_bf16 v[102:105], v[184:187], v[208:211], v[102:105]
	v_mfma_f32_16x16x32_bf16 v[98:101], v[192:195], v[208:211], v[98:101]
	v_mfma_f32_16x16x32_bf16 v[86:89], v[184:187], v[216:219], v[86:89]
	v_mfma_f32_16x16x32_bf16 v[82:85], v[192:195], v[216:219], v[82:85]
	v_mfma_f32_16x16x32_bf16 v[70:73], v[184:187], v[228:231], v[70:73]
	v_mfma_f32_16x16x32_bf16 v[66:69], v[192:195], v[228:231], v[66:69]
	s_barrier
	s_add_i32 s18, s63, s49
	v_lshl_add_u64 v[220:221], s[42:43], 0, v[134:135]
	s_mov_b32 m0, s18
	ds_read_b128 v[196:199], v173 offset:16384
	ds_read_b128 v[200:203], v173 offset:17408
	ds_read_b128 v[204:207], v173 offset:18432
	ds_read_b128 v[208:211], v173 offset:19456
	ds_read_b128 v[212:215], v173 offset:20480
	ds_read_b128 v[216:219], v173 offset:21504
	ds_read_b128 v[224:227], v173 offset:22528
	ds_read_b128 v[228:231], v173 offset:23552
	global_load_lds_dwordx4 v[220:221], off
	s_add_i32 m0, s18, 0x2000
	s_add_u32 s74, s42, 0x80000
	v_lshl_add_u64 v[232:233], s[42:43], 0, v[130:131]
	s_addc_u32 s75, s43, 0
	s_add_i32 s18, s64, s49
	global_load_lds_dwordx4 v[232:233], off
	v_lshl_add_u64 v[234:235], s[74:75], 0, v[134:135]
	s_mov_b32 m0, s18
	v_lshl_add_u64 v[236:237], s[44:45], 0, v[132:133]
	global_load_lds_dwordx4 v[234:235], off
	v_lshl_add_u64 v[234:235], s[74:75], 0, v[130:131]
	s_add_i32 m0, s18, 0x2000
	s_nop 0
	global_load_lds_dwordx4 v[234:235], off
	v_lshl_add_u64 v[234:235], s[44:45], 0, v[136:137]
	s_mov_b32 m0, s51
	s_nop 0
	global_load_lds_dwordx4 v[234:235], off
	s_mov_b32 m0, s52
	s_nop 0
	global_load_lds_dwordx4 v[236:237], off
	s_waitcnt vmcnt(8) lgkmcnt(0)
	s_barrier
; #define PG8_STAGE(bufoff, gbase, voff) do { _Pragma("unroll") for (int _i = 0; _i < 2; ++_i) \
;         __builtin_amdgcn_global_load_lds((const unsigned*)((const char*)(gbase) + (voff)[_i]), (PG8_LAS unsigned*)(lds + (bufoff) + ldsw + _i * 8192), 16, 0, 0); } while (0)
; #define PG8_LDA(dst, b, h) do { _Pragma("unroll") for (int m = 0; m < 4; ++m) _Pragma("unroll") for (int k = 0; k < 2; ++k) dst[m][k] = *(const PG8_LAS bf16x8*)(lds + PG8_SA(b, h) + aoff + m * 2048 + k * 1024); } while (0)
; #define PG8_LDB(dst, b, h) do { _Pragma("unroll") for (int n = 0; n < 2; ++n) _Pragma("unroll") for (int k = 0; k < 2; ++k) dst[n][k] = *(const PG8_LAS bf16x8*)(lds + PG8_SB(b, h) + boff + n * 2048 + k * 1024); } while (0)
; #define PG8_MMA(ai, bj, At, Bt) do { __builtin_amdgcn_s_setprio(1); _Pragma("unroll") for (int m = 0; m < 4; ++m) _Pragma("unroll") for (int n = 0; n < 2; ++n) _Pragma("unroll") for (int k = 0; k < 2; ++k) \
;         acc[ai][bj][m][n] = __builtin_amdgcn_mfma_f32_16x16x32_bf16(Bt[n][k], At[m][k], acc[ai][bj][m][n], 0, 0, 0); __builtin_amdgcn_s_setprio(0); } while (0)
; #define PG8_WAIT_V(n) asm volatile("s_waitcnt vmcnt(" #n ")" ::: "memory")
; #define PG8_WAIT_L(n) asm volatile("s_waitcnt lgkmcnt(" #n ")" ::: "memory")
; #define PG8_BAR __builtin_amdgcn_s_barrier()
; #define PG8_SCHED __builtin_amdgcn_sched_barrier(0)
; template <class Epi, class Sched, bool ALIGN_EPI = false, bool SP2 = false>
; __device__ __forceinline__ void gemm_phase(PG8_LAS unsigned char* lds, const Gemm g, const Sched& S, const Epi& E) {
;     ...
;             PG8_WAIT_V(8); PG8_WAIT_L(0); PG8_BAR; PG8_MMA(1, 0, At, B0); PG8_MMA(1, 1, At, B1); PG8_BAR; PG8_SCHED;
;             PG8_LDB(B0, 1, 0); PG8_LDB(B1, 1, 1); PG8_SCHED; PG8_LDA(At, 1, 0); PG8_STAGE(PG8_SA(0, 1), a2 + hA, voffA);
;             PG8_WAIT_V(8); PG8_WAIT_L(0); PG8_BAR; PG8_MMA(0, 0, At, B0); PG8_MMA(0, 1, At, B1); PG8_BAR; PG8_SCHED;
	v_mfma_f32_16x16x32_bf16 v[62:65], v[148:151], v[196:199], v[62:65]
	v_mfma_f32_16x16x32_bf16 v[58:61], v[156:159], v[196:199], v[58:61]
	v_mfma_f32_16x16x32_bf16 v[46:49], v[148:151], v[204:207], v[46:49]
	v_mfma_f32_16x16x32_bf16 v[42:45], v[156:159], v[204:207], v[42:45]
	v_mfma_f32_16x16x32_bf16 v[30:33], v[148:151], v[212:215], v[30:33]
	v_mfma_f32_16x16x32_bf16 v[26:29], v[156:159], v[212:215], v[26:29]
	v_mfma_f32_16x16x32_bf16 v[14:17], v[148:151], v[224:227], v[14:17]
	v_mfma_f32_16x16x32_bf16 v[10:13], v[156:159], v[224:227], v[10:13]
	v_mfma_f32_16x16x32_bf16 v[62:65], v[152:155], v[200:203], v[62:65]
	v_mfma_f32_16x16x32_bf16 v[58:61], v[160:163], v[200:203], v[58:61]
	v_mfma_f32_16x16x32_bf16 v[46:49], v[152:155], v[208:211], v[46:49]
	v_mfma_f32_16x16x32_bf16 v[42:45], v[160:163], v[208:211], v[42:45]
	v_mfma_f32_16x16x32_bf16 v[30:33], v[152:155], v[216:219], v[30:33]
	v_mfma_f32_16x16x32_bf16 v[26:29], v[160:163], v[216:219], v[26:29]
	v_mfma_f32_16x16x32_bf16 v[14:17], v[152:155], v[228:231], v[14:17]
	v_mfma_f32_16x16x32_bf16 v[10:13], v[160:163], v[228:231], v[10:13]
	v_mfma_f32_16x16x32_bf16 v[54:57], v[180:183], v[196:199], v[54:57]
	v_mfma_f32_16x16x32_bf16 v[50:53], v[188:191], v[196:199], v[50:53]
	v_mfma_f32_16x16x32_bf16 v[38:41], v[180:183], v[204:207], v[38:41]
	v_mfma_f32_16x16x32_bf16 v[34:37], v[188:191], v[204:207], v[34:37]
	v_mfma_f32_16x16x32_bf16 v[22:25], v[180:183], v[212:215], v[22:25]
	v_mfma_f32_16x16x32_bf16 v[18:21], v[188:191], v[212:215], v[18:21]
	v_mfma_f32_16x16x32_bf16 v[6:9], v[180:183], v[224:227], v[6:9]
	v_mfma_f32_16x16x32_bf16 v[2:5], v[188:191], v[224:227], v[2:5]
	v_mfma_f32_16x16x32_bf16 v[54:57], v[184:187], v[200:203], v[54:57]
	v_mfma_f32_16x16x32_bf16 v[50:53], v[192:195], v[200:203], v[50:53]
	v_mfma_f32_16x16x32_bf16 v[38:41], v[184:187], v[208:211], v[38:41]
	v_mfma_f32_16x16x32_bf16 v[34:37], v[192:195], v[208:211], v[34:37]
	v_mfma_f32_16x16x32_bf16 v[22:25], v[184:187], v[216:219], v[22:25]
	v_mfma_f32_16x16x32_bf16 v[18:21], v[192:195], v[216:219], v[18:21]
	v_mfma_f32_16x16x32_bf16 v[6:9], v[184:187], v[228:231], v[6:9]
	v_mfma_f32_16x16x32_bf16 v[2:5], v[192:195], v[228:231], v[2:5]
	s_barrier
	s_add_i32 s18, 0, 0x18000
	s_add_i32 s19, 0, 0x1c000
	v_add_u32_e32 v160, s18, v165
	v_add_u32_e32 v164, s19, v165
	ds_read_b128 v[148:151], v160
	ds_read_b128 v[152:155], v160 offset:1024
	ds_read_b128 v[156:159], v160 offset:2048
	ds_read_b128 v[160:163], v160 offset:3072
	ds_read_b128 v[180:183], v164
	ds_read_b128 v[184:187], v164 offset:1024
	ds_read_b128 v[188:191], v164 offset:2048
	ds_read_b128 v[192:195], v164 offset:3072
	s_add_u32 s44, s44, 0x80000
	s_addc_u32 s45, s45, 0
	s_mov_b32 m0, s53
	v_lshl_add_u64 v[238:239], s[44:45], 0, v[136:137]
	ds_read_b128 v[196:199], v173 offset:32768
	ds_read_b128 v[200:203], v173 offset:33792
	ds_read_b128 v[204:207], v173 offset:34816
	ds_read_b128 v[208:211], v173 offset:35840
	ds_read_b128 v[212:215], v173 offset:36864
	ds_read_b128 v[216:219], v173 offset:37888
	ds_read_b128 v[224:227], v173 offset:38912
	ds_read_b128 v[228:231], v173 offset:39936
	global_load_lds_dwordx4 v[238:239], off
	v_lshl_add_u64 v[238:239], s[44:45], 0, v[132:133]
	s_mov_b32 m0, s57
	s_nop 0
	global_load_lds_dwordx4 v[238:239], off
	s_waitcnt vmcnt(8) lgkmcnt(0)
	s_barrier
	v_mfma_f32_16x16x32_bf16 v[126:129], v[148:151], v[196:199], v[126:129]
	v_mfma_f32_16x16x32_bf16 v[122:125], v[156:159], v[196:199], v[122:125]
	v_mfma_f32_16x16x32_bf16 v[110:113], v[148:151], v[204:207], v[110:113]
	v_mfma_f32_16x16x32_bf16 v[106:109], v[156:159], v[204:207], v[106:109]
	v_mfma_f32_16x16x32_bf16 v[94:97], v[148:151], v[212:215], v[94:97]
	v_mfma_f32_16x16x32_bf16 v[90:93], v[156:159], v[212:215], v[90:93]
	v_mfma_f32_16x16x32_bf16 v[78:81], v[148:151], v[224:227], v[78:81]
	v_mfma_f32_16x16x32_bf16 v[74:77], v[156:159], v[224:227], v[74:77]
	v_mfma_f32_16x16x32_bf16 v[126:129], v[152:155], v[200:203], v[126:129]
	v_mfma_f32_16x16x32_bf16 v[122:125], v[160:163], v[200:203], v[122:125]
	v_mfma_f32_16x16x32_bf16 v[110:113], v[152:155], v[208:211], v[110:113]
	v_mfma_f32_16x16x32_bf16 v[106:109], v[160:163], v[208:211], v[106:109]
	v_mfma_f32_16x16x32_bf16 v[94:97], v[152:155], v[216:219], v[94:97]
	v_mfma_f32_16x16x32_bf16 v[90:93], v[160:163], v[216:219], v[90:93]
	v_mfma_f32_16x16x32_bf16 v[78:81], v[152:155], v[228:231], v[78:81]
	v_mfma_f32_16x16x32_bf16 v[74:77], v[160:163], v[228:231], v[74:77]
	v_mfma_f32_16x16x32_bf16 v[118:121], v[180:183], v[196:199], v[118:121]
	v_mfma_f32_16x16x32_bf16 v[114:117], v[188:191], v[196:199], v[114:117]
	v_mfma_f32_16x16x32_bf16 v[102:105], v[180:183], v[204:207], v[102:105]
	v_mfma_f32_16x16x32_bf16 v[98:101], v[188:191], v[204:207], v[98:101]
	v_mfma_f32_16x16x32_bf16 v[86:89], v[180:183], v[212:215], v[86:89]
	v_mfma_f32_16x16x32_bf16 v[82:85], v[188:191], v[212:215], v[82:85]
	v_mfma_f32_16x16x32_bf16 v[70:73], v[180:183], v[224:227], v[70:73]
	v_mfma_f32_16x16x32_bf16 v[66:69], v[188:191], v[224:227], v[66:69]
	v_mfma_f32_16x16x32_bf16 v[118:121], v[184:187], v[200:203], v[118:121]
	v_mfma_f32_16x16x32_bf16 v[114:117], v[192:195], v[200:203], v[114:117]
	v_mfma_f32_16x16x32_bf16 v[102:105], v[184:187], v[208:211], v[102:105]
	v_mfma_f32_16x16x32_bf16 v[98:101], v[192:195], v[208:211], v[98:101]
	v_mfma_f32_16x16x32_bf16 v[86:89], v[184:187], v[216:219], v[86:89]
	v_mfma_f32_16x16x32_bf16 v[82:85], v[192:195], v[216:219], v[82:85]
	v_mfma_f32_16x16x32_bf16 v[70:73], v[184:187], v[228:231], v[70:73]
	v_mfma_f32_16x16x32_bf16 v[66:69], v[192:195], v[228:231], v[66:69]
	s_barrier
; #define PG8_STAGE(bufoff, gbase, voff) do { _Pragma("unroll") for (int _i = 0; _i < 2; ++_i) \
;         __builtin_amdgcn_global_load_lds((const unsigned*)((const char*)(gbase) + (voff)[_i]), (PG8_LAS unsigned*)(lds + (bufoff) + ldsw + _i * 8192), 16, 0, 0); } while (0)
; #define PG8_LDA(dst, b, h) do { _Pragma("unroll") for (int m = 0; m < 4; ++m) _Pragma("unroll") for (int k = 0; k < 2; ++k) dst[m][k] = *(const PG8_LAS bf16x8*)(lds + PG8_SA(b, h) + aoff + m * 2048 + k * 1024); } while (0)
; #define PG8_MMA(ai, bj, At, Bt) do { __builtin_amdgcn_s_setprio(1); _Pragma("unroll") for (int m = 0; m < 4; ++m) _Pragma("unroll") for (int n = 0; n < 2; ++n) _Pragma("unroll") for (int k = 0; k < 2; ++k) \
;         acc[ai][bj][m][n] = __builtin_amdgcn_mfma_f32_16x16x32_bf16(Bt[n][k], At[m][k], acc[ai][bj][m][n], 0, 0, 0); __builtin_amdgcn_s_setprio(0); } while (0)
; #define PG8_WAIT_V(n) asm volatile("s_waitcnt vmcnt(" #n ")" ::: "memory")
; #define PG8_WAIT_L(n) asm volatile("s_waitcnt lgkmcnt(" #n ")" ::: "memory")
; #define PG8_BAR __builtin_amdgcn_s_barrier()
; #define PG8_SCHED __builtin_amdgcn_sched_barrier(0)
; template <class Epi, class Sched, bool ALIGN_EPI = false, bool SP2 = false>
; __device__ __forceinline__ void gemm_phase(PG8_LAS unsigned char* lds, const Gemm g, const Sched& S, const Epi& E) {
;     ...
;             PG8_LDA(At, 1, 1); PG8_STAGE(PG8_SB(1, 0), b3, voffB); PG8_STAGE(PG8_SB(1, 1), b3 + hB, voffB); PG8_STAGE(PG8_SA(1, 0), a3, voffA);
;             PG8_WAIT_V(8); PG8_WAIT_L(0); PG8_BAR; PG8_MMA(1, 0, At, B0); PG8_MMA(1, 1, At, B1); PG8_BAR; PG8_SCHED;
;     ...
;         if constexpr (ALIGN_EPI) { if (wr == 0) PG8_BAR; }
	s_add_i32 s18, s18, s49
	v_lshl_add_u64 v[220:221], v[220:221], 0, s[20:21]
	s_mov_b32 m0, s18
	ds_read_b128 v[196:199], v173 offset:49152
	ds_read_b128 v[200:203], v173 offset:50176
	ds_read_b128 v[204:207], v173 offset:51200
	ds_read_b128 v[208:211], v173 offset:52224
	ds_read_b128 v[212:215], v173 offset:53248
	ds_read_b128 v[216:219], v173 offset:54272
	ds_read_b128 v[224:227], v173 offset:55296
	ds_read_b128 v[228:231], v173 offset:56320
	global_load_lds_dwordx4 v[220:221], off
	s_add_i32 m0, s18, 0x2000
	s_add_u32 s42, s42, 0x80080
	v_lshl_add_u64 v[220:221], v[232:233], 0, s[20:21]
	s_addc_u32 s43, s43, 0
	s_add_i32 s18, s19, s49
	global_load_lds_dwordx4 v[220:221], off
	v_lshl_add_u64 v[220:221], s[42:43], 0, v[134:135]
	s_mov_b32 m0, s18
	s_nop 0
	global_load_lds_dwordx4 v[220:221], off
	v_lshl_add_u64 v[220:221], s[42:43], 0, v[130:131]
	s_add_i32 m0, s18, 0x2000
	s_nop 0
	global_load_lds_dwordx4 v[220:221], off
	v_lshl_add_u64 v[220:221], v[234:235], 0, s[20:21]
	s_mov_b32 m0, s60
	s_nop 0
	global_load_lds_dwordx4 v[220:221], off
	v_lshl_add_u64 v[220:221], v[236:237], 0, s[20:21]
	s_mov_b32 m0, s61
	s_nop 0
	global_load_lds_dwordx4 v[220:221], off
	s_waitcnt vmcnt(8) lgkmcnt(0)
	s_barrier
	v_mfma_f32_16x16x32_bf16 v[62:65], v[148:151], v[196:199], v[62:65]
	v_mfma_f32_16x16x32_bf16 v[58:61], v[156:159], v[196:199], v[58:61]
	v_mfma_f32_16x16x32_bf16 v[46:49], v[148:151], v[204:207], v[46:49]
	v_mfma_f32_16x16x32_bf16 v[42:45], v[156:159], v[204:207], v[42:45]
	v_mfma_f32_16x16x32_bf16 v[30:33], v[148:151], v[212:215], v[30:33]
	v_mfma_f32_16x16x32_bf16 v[26:29], v[156:159], v[212:215], v[26:29]
	v_mfma_f32_16x16x32_bf16 v[14:17], v[148:151], v[224:227], v[14:17]
	v_mfma_f32_16x16x32_bf16 v[10:13], v[156:159], v[224:227], v[10:13]
	v_mfma_f32_16x16x32_bf16 v[62:65], v[152:155], v[200:203], v[62:65]
	v_mfma_f32_16x16x32_bf16 v[58:61], v[160:163], v[200:203], v[58:61]
	v_mfma_f32_16x16x32_bf16 v[46:49], v[152:155], v[208:211], v[46:49]
	v_mfma_f32_16x16x32_bf16 v[42:45], v[160:163], v[208:211], v[42:45]
	v_mfma_f32_16x16x32_bf16 v[30:33], v[152:155], v[216:219], v[30:33]
	v_mfma_f32_16x16x32_bf16 v[26:29], v[160:163], v[216:219], v[26:29]
	v_mfma_f32_16x16x32_bf16 v[14:17], v[152:155], v[228:231], v[14:17]
	v_mfma_f32_16x16x32_bf16 v[10:13], v[160:163], v[228:231], v[10:13]
	v_mfma_f32_16x16x32_bf16 v[54:57], v[180:183], v[196:199], v[54:57]
	v_mfma_f32_16x16x32_bf16 v[50:53], v[188:191], v[196:199], v[50:53]
	v_mfma_f32_16x16x32_bf16 v[38:41], v[180:183], v[204:207], v[38:41]
	v_mfma_f32_16x16x32_bf16 v[34:37], v[188:191], v[204:207], v[34:37]
	v_mfma_f32_16x16x32_bf16 v[22:25], v[180:183], v[212:215], v[22:25]
	v_mfma_f32_16x16x32_bf16 v[18:21], v[188:191], v[212:215], v[18:21]
	v_mfma_f32_16x16x32_bf16 v[6:9], v[180:183], v[224:227], v[6:9]
	v_mfma_f32_16x16x32_bf16 v[2:5], v[188:191], v[224:227], v[2:5]
	v_mfma_f32_16x16x32_bf16 v[54:57], v[184:187], v[200:203], v[54:57]
	v_mfma_f32_16x16x32_bf16 v[50:53], v[192:195], v[200:203], v[50:53]
	v_mfma_f32_16x16x32_bf16 v[38:41], v[184:187], v[208:211], v[38:41]
	v_mfma_f32_16x16x32_bf16 v[34:37], v[192:195], v[208:211], v[34:37]
	v_mfma_f32_16x16x32_bf16 v[22:25], v[184:187], v[216:219], v[22:25]
	v_mfma_f32_16x16x32_bf16 v[18:21], v[192:195], v[216:219], v[18:21]
	v_mfma_f32_16x16x32_bf16 v[6:9], v[184:187], v[228:231], v[6:9]
	v_mfma_f32_16x16x32_bf16 v[2:5], v[192:195], v[228:231], v[2:5]
	s_barrier
	s_add_i32 s72, s72, 2
	s_add_u32 s8, s8, 0x100
	s_addc_u32 s9, s9, 0
	s_add_u32 s70, s70, 0x100
	s_addc_u32 s71, s71, 0
	s_cmp_gt_u32 s72, 29
	s_cbranch_scc0 .LBB0_1048
	s_and_b64 vcc, exec, s[22:23]
	s_cbranch_vccz .LBB0_1051
	s_barrier

; #define PG8_STAGE(bufoff, gbase, voff) do { _Pragma("unroll") for (int _i = 0; _i < 2; ++_i) \
;         __builtin_amdgcn_global_load_lds((const unsigned*)((const char*)(gbase) + (voff)[_i]), (PG8_LAS unsigned*)(lds + (bufoff) + ldsw + _i * 8192), 16, 0, 0); } while (0)
; #define PG8_LDA(dst, b, h) do { _Pragma("unroll") for (int m = 0; m < 4; ++m) _Pragma("unroll") for (int k = 0; k < 2; ++k) dst[m][k] = *(const PG8_LAS bf16x8*)(lds + PG8_SA(b, h) + aoff + m * 2048 + k * 1024); } while (0)
; #define PG8_LDB(dst, b, h) do { _Pragma("unroll") for (int n = 0; n < 2; ++n) _Pragma("unroll") for (int k = 0; k < 2; ++k) dst[n][k] = *(const PG8_LAS bf16x8*)(lds + PG8_SB(b, h) + boff + n * 2048 + k * 1024); } while (0)
; #define PG8_MMA(ai, bj, At, Bt) do { __builtin_amdgcn_s_setprio(1); _Pragma("unroll") for (int m = 0; m < 4; ++m) _Pragma("unroll") for (int n = 0; n < 2; ++n) _Pragma("unroll") for (int k = 0; k < 2; ++k) \
;         acc[ai][bj][m][n] = __builtin_amdgcn_mfma_f32_16x16x32_bf16(Bt[n][k], At[m][k], acc[ai][bj][m][n], 0, 0, 0); __builtin_amdgcn_s_setprio(0); } while (0)
; #define PG8_WAIT_V(n) asm volatile("s_waitcnt vmcnt(" #n ")" ::: "memory")
; #define PG8_WAIT_L(n) asm volatile("s_waitcnt lgkmcnt(" #n ")" ::: "memory")
; template <class Epi, class Sched, bool ALIGN_EPI = false, bool SP2 = false>
; __device__ __forceinline__ void gemm_phase(PG8_LAS unsigned char* lds, const Gemm g, const Sched& S, const Epi& E) {
;     ...
;             const bool last = (t == nt - 2);
;             const char* a1 = cA + (size_t)(t + 1) * kstep;
;             const char* a2 = last ? nA : cA + (size_t)(t + 2) * kstep; const char* b2 = last ? nB : cB + (size_t)(t + 2) * kstep;
;             const char* a3 = a2 + kstep; const char* b3 = b2 + kstep;
;             if (last && has_next) S.a_ready(nxt);
;             if constexpr (SP2) {
;             PG8_LDB(B0, 0, 0); PG8_LDB(B1, 0, 1); PG8_SCHED; PG8_LDA(At, 0, 0); PG8_STAGE(PG8_SA(1, 1), a1 + hA, voffA);
;             PG8_WAIT_V(8); PG8_WAIT_L(0); PG8_BAR; PG8_MMA(0, 0, At, B0); PG8_MMA(0, 1, At, B1); PG8_BAR; PG8_SCHED;
;             PG8_LDA(At, 0, 1); PG8_STAGE(PG8_SB(0, 0), b2, voffB); PG8_STAGE(PG8_SB(0, 1), b2 + hB, voffB); PG8_STAGE(PG8_SA(0, 0), a2, voffA);
;             PG8_WAIT_V(8); PG8_WAIT_L(0); PG8_BAR; PG8_MMA(1, 0, At, B0); PG8_MMA(1, 1, At, B1); PG8_BAR; PG8_SCHED;
.LBB0_1127:
	ds_read_b128 v[130:133], v190
	ds_read_b128 v[134:137], v190 offset:1024
	ds_read_b128 v[138:141], v190 offset:2048
	ds_read_b128 v[142:145], v190 offset:3072
	ds_read_b128 v[146:149], v191
	ds_read_b128 v[150:153], v191 offset:1024
	ds_read_b128 v[170:173], v191 offset:2048
	ds_read_b128 v[174:177], v191 offset:3072
	s_add_u32 s36, s24, 0x100
	s_addc_u32 s37, s25, 0
	s_cmpk_eq_i32 s63, 0x54
	s_cselect_b32 s41, s9, s37
	s_cselect_b32 s40, s8, s36
	s_cselect_b32 s39, s23, s62
	s_cselect_b32 s38, s22, s61
	v_lshl_add_u64 v[186:187], s[24:25], 0, v[162:163]
	s_add_i32 m0, s46, 0xc000
	ds_read_b128 v[178:181], v192
	ds_read_b128 v[182:185], v192 offset:1024
	ds_read_b128 v[194:197], v192 offset:2048
	ds_read_b128 v[198:201], v192 offset:3072
	ds_read_b128 v[202:205], v192 offset:4096
	ds_read_b128 v[206:209], v192 offset:5120
	ds_read_b128 v[210:213], v192 offset:6144
	ds_read_b128 v[214:217], v192 offset:7168
	global_load_lds_dwordx4 v[186:187], off
	v_lshl_add_u64 v[186:187], s[24:25], 0, v[164:165]
	s_add_i32 m0, s46, 0xe000
	s_nop 0
	global_load_lds_dwordx4 v[186:187], off
	s_waitcnt vmcnt(8) lgkmcnt(0)
	s_barrier
	v_mfma_f32_16x16x32_bf16 v[126:129], v[130:133], v[178:181], v[126:129]
	v_mfma_f32_16x16x32_bf16 v[122:125], v[138:141], v[178:181], v[122:125]
	v_mfma_f32_16x16x32_bf16 v[110:113], v[130:133], v[194:197], v[110:113]
	v_mfma_f32_16x16x32_bf16 v[106:109], v[138:141], v[194:197], v[106:109]
	v_mfma_f32_16x16x32_bf16 v[94:97], v[130:133], v[202:205], v[94:97]
	v_mfma_f32_16x16x32_bf16 v[90:93], v[138:141], v[202:205], v[90:93]
	v_mfma_f32_16x16x32_bf16 v[78:81], v[130:133], v[210:213], v[78:81]
	v_mfma_f32_16x16x32_bf16 v[74:77], v[138:141], v[210:213], v[74:77]
	v_mfma_f32_16x16x32_bf16 v[126:129], v[134:137], v[182:185], v[126:129]
	v_mfma_f32_16x16x32_bf16 v[122:125], v[142:145], v[182:185], v[122:125]
	v_mfma_f32_16x16x32_bf16 v[110:113], v[134:137], v[198:201], v[110:113]
	v_mfma_f32_16x16x32_bf16 v[106:109], v[142:145], v[198:201], v[106:109]
	v_mfma_f32_16x16x32_bf16 v[94:97], v[134:137], v[206:209], v[94:97]
	v_mfma_f32_16x16x32_bf16 v[90:93], v[142:145], v[206:209], v[90:93]
	v_mfma_f32_16x16x32_bf16 v[78:81], v[134:137], v[214:217], v[78:81]
	v_mfma_f32_16x16x32_bf16 v[74:77], v[142:145], v[214:217], v[74:77]
	v_mfma_f32_16x16x32_bf16 v[118:121], v[146:149], v[178:181], v[118:121]
	v_mfma_f32_16x16x32_bf16 v[114:117], v[170:173], v[178:181], v[114:117]
	v_mfma_f32_16x16x32_bf16 v[102:105], v[146:149], v[194:197], v[102:105]
	v_mfma_f32_16x16x32_bf16 v[98:101], v[170:173], v[194:197], v[98:101]
	v_mfma_f32_16x16x32_bf16 v[86:89], v[146:149], v[202:205], v[86:89]
	v_mfma_f32_16x16x32_bf16 v[82:85], v[170:173], v[202:205], v[82:85]
	v_mfma_f32_16x16x32_bf16 v[70:73], v[146:149], v[210:213], v[70:73]
	v_mfma_f32_16x16x32_bf16 v[66:69], v[170:173], v[210:213], v[66:69]
	v_mfma_f32_16x16x32_bf16 v[118:121], v[150:153], v[182:185], v[118:121]
	v_mfma_f32_16x16x32_bf16 v[114:117], v[174:177], v[182:185], v[114:117]
	v_mfma_f32_16x16x32_bf16 v[102:105], v[150:153], v[198:201], v[102:105]
	v_mfma_f32_16x16x32_bf16 v[98:101], v[174:177], v[198:201], v[98:101]
	v_mfma_f32_16x16x32_bf16 v[86:89], v[150:153], v[206:209], v[86:89]
	v_mfma_f32_16x16x32_bf16 v[82:85], v[174:177], v[206:209], v[82:85]
	v_mfma_f32_16x16x32_bf16 v[70:73], v[150:153], v[214:217], v[70:73]
	v_mfma_f32_16x16x32_bf16 v[66:69], v[174:177], v[214:217], v[66:69]
	s_barrier
	s_add_i32 s18, s55, s45
	v_lshl_add_u64 v[186:187], s[38:39], 0, v[156:157]
	s_mov_b32 m0, s18
	ds_read_b128 v[178:181], v192 offset:16384
	ds_read_b128 v[182:185], v192 offset:17408
	ds_read_b128 v[194:197], v192 offset:18432
	ds_read_b128 v[198:201], v192 offset:19456
	ds_read_b128 v[202:205], v192 offset:20480
	ds_read_b128 v[206:209], v192 offset:21504
	ds_read_b128 v[210:213], v192 offset:22528
	ds_read_b128 v[214:217], v192 offset:23552
	global_load_lds_dwordx4 v[186:187], off
	s_add_i32 m0, s18, 0x2000
	s_add_u32 s24, s38, 0x160000
	v_lshl_add_u64 v[218:219], s[38:39], 0, v[160:161]
	s_addc_u32 s25, s39, 0
	s_add_i32 s18, s56, s45
	global_load_lds_dwordx4 v[218:219], off
	v_lshl_add_u64 v[220:221], s[24:25], 0, v[156:157]
	s_mov_b32 m0, s18
	v_lshl_add_u64 v[224:225], s[40:41], 0, v[158:159]
	global_load_lds_dwordx4 v[220:221], off
	v_lshl_add_u64 v[220:221], s[24:25], 0, v[160:161]
	s_add_i32 m0, s18, 0x2000
	s_nop 0
	global_load_lds_dwordx4 v[220:221], off
	v_lshl_add_u64 v[220:221], s[40:41], 0, v[154:155]
	s_mov_b32 m0, s46
	s_nop 0
	global_load_lds_dwordx4 v[220:221], off
	s_mov_b32 m0, s47
	s_nop 0
	global_load_lds_dwordx4 v[224:225], off
	s_waitcnt vmcnt(8) lgkmcnt(0)
	s_barrier
; #define PG8_STAGE(bufoff, gbase, voff) do { _Pragma("unroll") for (int _i = 0; _i < 2; ++_i) \
;         __builtin_amdgcn_global_load_lds((const unsigned*)((const char*)(gbase) + (voff)[_i]), (PG8_LAS unsigned*)(lds + (bufoff) + ldsw + _i * 8192), 16, 0, 0); } while (0)
; #define PG8_LDA(dst, b, h) do { _Pragma("unroll") for (int m = 0; m < 4; ++m) _Pragma("unroll") for (int k = 0; k < 2; ++k) dst[m][k] = *(const PG8_LAS bf16x8*)(lds + PG8_SA(b, h) + aoff + m * 2048 + k * 1024); } while (0)
; #define PG8_LDB(dst, b, h) do { _Pragma("unroll") for (int n = 0; n < 2; ++n) _Pragma("unroll") for (int k = 0; k < 2; ++k) dst[n][k] = *(const PG8_LAS bf16x8*)(lds + PG8_SB(b, h) + boff + n * 2048 + k * 1024); } while (0)
; #define PG8_MMA(ai, bj, At, Bt) do { __builtin_amdgcn_s_setprio(1); _Pragma("unroll") for (int m = 0; m < 4; ++m) _Pragma("unroll") for (int n = 0; n < 2; ++n) _Pragma("unroll") for (int k = 0; k < 2; ++k) \
;         acc[ai][bj][m][n] = __builtin_amdgcn_mfma_f32_16x16x32_bf16(Bt[n][k], At[m][k], acc[ai][bj][m][n], 0, 0, 0); __builtin_amdgcn_s_setprio(0); } while (0)
; #define PG8_WAIT_V(n) asm volatile("s_waitcnt vmcnt(" #n ")" ::: "memory")
; #define PG8_WAIT_L(n) asm volatile("s_waitcnt lgkmcnt(" #n ")" ::: "memory")
; #define PG8_BAR __builtin_amdgcn_s_barrier()
; #define PG8_SCHED __builtin_amdgcn_sched_barrier(0)
; template <class Epi, class Sched, bool ALIGN_EPI = false, bool SP2 = false>
; __device__ __forceinline__ void gemm_phase(PG8_LAS unsigned char* lds, const Gemm g, const Sched& S, const Epi& E) {
;     ...
;             PG8_WAIT_V(8); PG8_WAIT_L(0); PG8_BAR; PG8_MMA(1, 0, At, B0); PG8_MMA(1, 1, At, B1); PG8_BAR; PG8_SCHED;
;             PG8_LDB(B0, 1, 0); PG8_LDB(B1, 1, 1); PG8_SCHED; PG8_LDA(At, 1, 0); PG8_STAGE(PG8_SA(0, 1), a2 + hA, voffA);
;             PG8_WAIT_V(8); PG8_WAIT_L(0); PG8_BAR; PG8_MMA(0, 0, At, B0); PG8_MMA(0, 1, At, B1); PG8_BAR; PG8_SCHED;
	v_mfma_f32_16x16x32_bf16 v[62:65], v[130:133], v[178:181], v[62:65]
	v_mfma_f32_16x16x32_bf16 v[58:61], v[138:141], v[178:181], v[58:61]
	v_mfma_f32_16x16x32_bf16 v[46:49], v[130:133], v[194:197], v[46:49]
	v_mfma_f32_16x16x32_bf16 v[42:45], v[138:141], v[194:197], v[42:45]
	v_mfma_f32_16x16x32_bf16 v[30:33], v[130:133], v[202:205], v[30:33]
	v_mfma_f32_16x16x32_bf16 v[26:29], v[138:141], v[202:205], v[26:29]
	v_mfma_f32_16x16x32_bf16 v[14:17], v[130:133], v[210:213], v[14:17]
	v_mfma_f32_16x16x32_bf16 v[10:13], v[138:141], v[210:213], v[10:13]
	v_mfma_f32_16x16x32_bf16 v[62:65], v[134:137], v[182:185], v[62:65]
	v_mfma_f32_16x16x32_bf16 v[58:61], v[142:145], v[182:185], v[58:61]
	v_mfma_f32_16x16x32_bf16 v[46:49], v[134:137], v[198:201], v[46:49]
	v_mfma_f32_16x16x32_bf16 v[42:45], v[142:145], v[198:201], v[42:45]
	v_mfma_f32_16x16x32_bf16 v[30:33], v[134:137], v[206:209], v[30:33]
	v_mfma_f32_16x16x32_bf16 v[26:29], v[142:145], v[206:209], v[26:29]
	v_mfma_f32_16x16x32_bf16 v[14:17], v[134:137], v[214:217], v[14:17]
	v_mfma_f32_16x16x32_bf16 v[10:13], v[142:145], v[214:217], v[10:13]
	v_mfma_f32_16x16x32_bf16 v[54:57], v[146:149], v[178:181], v[54:57]
	v_mfma_f32_16x16x32_bf16 v[50:53], v[170:173], v[178:181], v[50:53]
	v_mfma_f32_16x16x32_bf16 v[38:41], v[146:149], v[194:197], v[38:41]
	v_mfma_f32_16x16x32_bf16 v[34:37], v[170:173], v[194:197], v[34:37]
	v_mfma_f32_16x16x32_bf16 v[22:25], v[146:149], v[202:205], v[22:25]
	v_mfma_f32_16x16x32_bf16 v[18:21], v[170:173], v[202:205], v[18:21]
	v_mfma_f32_16x16x32_bf16 v[6:9], v[146:149], v[210:213], v[6:9]
	v_mfma_f32_16x16x32_bf16 v[2:5], v[170:173], v[210:213], v[2:5]
	v_mfma_f32_16x16x32_bf16 v[54:57], v[150:153], v[182:185], v[54:57]
	v_mfma_f32_16x16x32_bf16 v[50:53], v[174:177], v[182:185], v[50:53]
	v_mfma_f32_16x16x32_bf16 v[38:41], v[150:153], v[198:201], v[38:41]
	v_mfma_f32_16x16x32_bf16 v[34:37], v[174:177], v[198:201], v[34:37]
	v_mfma_f32_16x16x32_bf16 v[22:25], v[150:153], v[206:209], v[22:25]
	v_mfma_f32_16x16x32_bf16 v[18:21], v[174:177], v[206:209], v[18:21]
	v_mfma_f32_16x16x32_bf16 v[6:9], v[150:153], v[214:217], v[6:9]
	v_mfma_f32_16x16x32_bf16 v[2:5], v[174:177], v[214:217], v[2:5]
	s_barrier
	s_add_i32 s18, 0, 0x18000
	s_add_i32 s19, 0, 0x1c000
	v_add_u32_e32 v142, s18, v188
	v_add_u32_e32 v174, s19, v188
	ds_read_b128 v[130:133], v142
	ds_read_b128 v[134:137], v142 offset:1024
	ds_read_b128 v[138:141], v142 offset:2048
	ds_read_b128 v[142:145], v142 offset:3072
	ds_read_b128 v[146:149], v174
	ds_read_b128 v[150:153], v174 offset:1024
	ds_read_b128 v[170:173], v174 offset:2048
	ds_read_b128 v[174:177], v174 offset:3072
	s_add_u32 s24, s40, 0x160000
	s_addc_u32 s25, s41, 0
	s_mov_b32 m0, s48
	v_lshl_add_u64 v[226:227], s[24:25], 0, v[154:155]
	ds_read_b128 v[178:181], v192 offset:32768
	ds_read_b128 v[182:185], v192 offset:33792
	ds_read_b128 v[194:197], v192 offset:34816
	ds_read_b128 v[198:201], v192 offset:35840
	ds_read_b128 v[202:205], v192 offset:36864
	ds_read_b128 v[206:209], v192 offset:37888
	ds_read_b128 v[210:213], v192 offset:38912
	ds_read_b128 v[214:217], v192 offset:39936
	global_load_lds_dwordx4 v[226:227], off
	v_lshl_add_u64 v[226:227], s[24:25], 0, v[158:159]
	s_mov_b32 m0, s49
	s_nop 0
	global_load_lds_dwordx4 v[226:227], off
	s_waitcnt vmcnt(8) lgkmcnt(0)
	s_barrier
	v_mfma_f32_16x16x32_bf16 v[126:129], v[130:133], v[178:181], v[126:129]
	v_mfma_f32_16x16x32_bf16 v[122:125], v[138:141], v[178:181], v[122:125]
	v_mfma_f32_16x16x32_bf16 v[110:113], v[130:133], v[194:197], v[110:113]
	v_mfma_f32_16x16x32_bf16 v[106:109], v[138:141], v[194:197], v[106:109]
	v_mfma_f32_16x16x32_bf16 v[94:97], v[130:133], v[202:205], v[94:97]
	v_mfma_f32_16x16x32_bf16 v[90:93], v[138:141], v[202:205], v[90:93]
	v_mfma_f32_16x16x32_bf16 v[78:81], v[130:133], v[210:213], v[78:81]
	v_mfma_f32_16x16x32_bf16 v[74:77], v[138:141], v[210:213], v[74:77]
	v_mfma_f32_16x16x32_bf16 v[126:129], v[134:137], v[182:185], v[126:129]
	v_mfma_f32_16x16x32_bf16 v[122:125], v[142:145], v[182:185], v[122:125]
	v_mfma_f32_16x16x32_bf16 v[110:113], v[134:137], v[198:201], v[110:113]
	v_mfma_f32_16x16x32_bf16 v[106:109], v[142:145], v[198:201], v[106:109]
	v_mfma_f32_16x16x32_bf16 v[94:97], v[134:137], v[206:209], v[94:97]
	v_mfma_f32_16x16x32_bf16 v[90:93], v[142:145], v[206:209], v[90:93]
	v_mfma_f32_16x16x32_bf16 v[78:81], v[134:137], v[214:217], v[78:81]
	v_mfma_f32_16x16x32_bf16 v[74:77], v[142:145], v[214:217], v[74:77]
	v_mfma_f32_16x16x32_bf16 v[118:121], v[146:149], v[178:181], v[118:121]
	v_mfma_f32_16x16x32_bf16 v[114:117], v[170:173], v[178:181], v[114:117]
	v_mfma_f32_16x16x32_bf16 v[102:105], v[146:149], v[194:197], v[102:105]
	v_mfma_f32_16x16x32_bf16 v[98:101], v[170:173], v[194:197], v[98:101]
	v_mfma_f32_16x16x32_bf16 v[86:89], v[146:149], v[202:205], v[86:89]
	v_mfma_f32_16x16x32_bf16 v[82:85], v[170:173], v[202:205], v[82:85]
	v_mfma_f32_16x16x32_bf16 v[70:73], v[146:149], v[210:213], v[70:73]
	v_mfma_f32_16x16x32_bf16 v[66:69], v[170:173], v[210:213], v[66:69]
	v_mfma_f32_16x16x32_bf16 v[118:121], v[150:153], v[182:185], v[118:121]
	v_mfma_f32_16x16x32_bf16 v[114:117], v[174:177], v[182:185], v[114:117]
	v_mfma_f32_16x16x32_bf16 v[102:105], v[150:153], v[198:201], v[102:105]
	v_mfma_f32_16x16x32_bf16 v[98:101], v[174:177], v[198:201], v[98:101]
	v_mfma_f32_16x16x32_bf16 v[86:89], v[150:153], v[206:209], v[86:89]
	v_mfma_f32_16x16x32_bf16 v[82:85], v[174:177], v[206:209], v[82:85]
	v_mfma_f32_16x16x32_bf16 v[70:73], v[150:153], v[214:217], v[70:73]
	v_mfma_f32_16x16x32_bf16 v[66:69], v[174:177], v[214:217], v[66:69]
	s_barrier
; #define PG8_STAGE(bufoff, gbase, voff) do { _Pragma("unroll") for (int _i = 0; _i < 2; ++_i) \
;         __builtin_amdgcn_global_load_lds((const unsigned*)((const char*)(gbase) + (voff)[_i]), (PG8_LAS unsigned*)(lds + (bufoff) + ldsw + _i * 8192), 16, 0, 0); } while (0)
; #define PG8_LDA(dst, b, h) do { _Pragma("unroll") for (int m = 0; m < 4; ++m) _Pragma("unroll") for (int k = 0; k < 2; ++k) dst[m][k] = *(const PG8_LAS bf16x8*)(lds + PG8_SA(b, h) + aoff + m * 2048 + k * 1024); } while (0)
; #define PG8_MMA(ai, bj, At, Bt) do { __builtin_amdgcn_s_setprio(1); _Pragma("unroll") for (int m = 0; m < 4; ++m) _Pragma("unroll") for (int n = 0; n < 2; ++n) _Pragma("unroll") for (int k = 0; k < 2; ++k) \
;         acc[ai][bj][m][n] = __builtin_amdgcn_mfma_f32_16x16x32_bf16(Bt[n][k], At[m][k], acc[ai][bj][m][n], 0, 0, 0); __builtin_amdgcn_s_setprio(0); } while (0)
; #define PG8_WAIT_V(n) asm volatile("s_waitcnt vmcnt(" #n ")" ::: "memory")
; #define PG8_WAIT_L(n) asm volatile("s_waitcnt lgkmcnt(" #n ")" ::: "memory")
; #define PG8_BAR __builtin_amdgcn_s_barrier()
; #define PG8_SCHED __builtin_amdgcn_sched_barrier(0)
; template <class Epi, class Sched, bool ALIGN_EPI = false, bool SP2 = false>
; __device__ __forceinline__ void gemm_phase(PG8_LAS unsigned char* lds, const Gemm g, const Sched& S, const Epi& E) {
;     ...
;             PG8_LDA(At, 1, 1); PG8_STAGE(PG8_SB(1, 0), b3, voffB); PG8_STAGE(PG8_SB(1, 1), b3 + hB, voffB); PG8_STAGE(PG8_SA(1, 0), a3, voffA);
;             PG8_WAIT_V(8); PG8_WAIT_L(0); PG8_BAR; PG8_MMA(1, 0, At, B0); PG8_MMA(1, 1, At, B1); PG8_BAR; PG8_SCHED;
;     ...
;         if constexpr (ALIGN_EPI) { if (wr == 0) PG8_BAR; }
	s_add_i32 s18, s18, s45
	v_lshl_add_u64 v[186:187], v[186:187], 0, s[16:17]
	s_mov_b32 m0, s18
	ds_read_b128 v[178:181], v192 offset:49152
	ds_read_b128 v[182:185], v192 offset:50176
	ds_read_b128 v[194:197], v192 offset:51200
	ds_read_b128 v[198:201], v192 offset:52224
	ds_read_b128 v[202:205], v192 offset:53248
	ds_read_b128 v[206:209], v192 offset:54272
	ds_read_b128 v[210:213], v192 offset:55296
	ds_read_b128 v[214:217], v192 offset:56320
	global_load_lds_dwordx4 v[186:187], off
	s_add_i32 m0, s18, 0x2000
	s_add_u32 s24, s38, 0x160080
	v_lshl_add_u64 v[186:187], v[218:219], 0, s[16:17]
	s_addc_u32 s25, s39, 0
	s_add_i32 s18, s19, s45
	global_load_lds_dwordx4 v[186:187], off
	v_lshl_add_u64 v[186:187], s[24:25], 0, v[156:157]
	s_mov_b32 m0, s18
	s_nop 0
	global_load_lds_dwordx4 v[186:187], off
	v_lshl_add_u64 v[186:187], s[24:25], 0, v[160:161]
	s_add_i32 m0, s18, 0x2000
	s_nop 0
	global_load_lds_dwordx4 v[186:187], off
	v_lshl_add_u64 v[186:187], v[220:221], 0, s[16:17]
	s_mov_b32 m0, s52
	s_nop 0
	global_load_lds_dwordx4 v[186:187], off
	v_lshl_add_u64 v[186:187], v[224:225], 0, s[16:17]
	s_mov_b32 m0, s53
	s_nop 0
	global_load_lds_dwordx4 v[186:187], off
	s_waitcnt vmcnt(8) lgkmcnt(0)
	s_barrier
	v_mfma_f32_16x16x32_bf16 v[62:65], v[130:133], v[178:181], v[62:65]
	v_mfma_f32_16x16x32_bf16 v[58:61], v[138:141], v[178:181], v[58:61]
	v_mfma_f32_16x16x32_bf16 v[46:49], v[130:133], v[194:197], v[46:49]
	v_mfma_f32_16x16x32_bf16 v[42:45], v[138:141], v[194:197], v[42:45]
	v_mfma_f32_16x16x32_bf16 v[30:33], v[130:133], v[202:205], v[30:33]
	v_mfma_f32_16x16x32_bf16 v[26:29], v[138:141], v[202:205], v[26:29]
	v_mfma_f32_16x16x32_bf16 v[14:17], v[130:133], v[210:213], v[14:17]
	v_mfma_f32_16x16x32_bf16 v[10:13], v[138:141], v[210:213], v[10:13]
	v_mfma_f32_16x16x32_bf16 v[62:65], v[134:137], v[182:185], v[62:65]
	v_mfma_f32_16x16x32_bf16 v[58:61], v[142:145], v[182:185], v[58:61]
	v_mfma_f32_16x16x32_bf16 v[46:49], v[134:137], v[198:201], v[46:49]
	v_mfma_f32_16x16x32_bf16 v[42:45], v[142:145], v[198:201], v[42:45]
	v_mfma_f32_16x16x32_bf16 v[30:33], v[134:137], v[206:209], v[30:33]
	v_mfma_f32_16x16x32_bf16 v[26:29], v[142:145], v[206:209], v[26:29]
	v_mfma_f32_16x16x32_bf16 v[14:17], v[134:137], v[214:217], v[14:17]
	v_mfma_f32_16x16x32_bf16 v[10:13], v[142:145], v[214:217], v[10:13]
	v_mfma_f32_16x16x32_bf16 v[54:57], v[146:149], v[178:181], v[54:57]
	v_mfma_f32_16x16x32_bf16 v[50:53], v[170:173], v[178:181], v[50:53]
	v_mfma_f32_16x16x32_bf16 v[38:41], v[146:149], v[194:197], v[38:41]
	v_mfma_f32_16x16x32_bf16 v[34:37], v[170:173], v[194:197], v[34:37]
	v_mfma_f32_16x16x32_bf16 v[22:25], v[146:149], v[202:205], v[22:25]
	v_mfma_f32_16x16x32_bf16 v[18:21], v[170:173], v[202:205], v[18:21]
	v_mfma_f32_16x16x32_bf16 v[6:9], v[146:149], v[210:213], v[6:9]
	v_mfma_f32_16x16x32_bf16 v[2:5], v[170:173], v[210:213], v[2:5]
	v_mfma_f32_16x16x32_bf16 v[54:57], v[150:153], v[182:185], v[54:57]
	v_mfma_f32_16x16x32_bf16 v[50:53], v[174:177], v[182:185], v[50:53]
	v_mfma_f32_16x16x32_bf16 v[38:41], v[150:153], v[198:201], v[38:41]
	v_mfma_f32_16x16x32_bf16 v[34:37], v[174:177], v[198:201], v[34:37]
	v_mfma_f32_16x16x32_bf16 v[22:25], v[150:153], v[206:209], v[22:25]
	v_mfma_f32_16x16x32_bf16 v[18:21], v[174:177], v[206:209], v[18:21]
	v_mfma_f32_16x16x32_bf16 v[6:9], v[150:153], v[214:217], v[6:9]
	v_mfma_f32_16x16x32_bf16 v[2:5], v[174:177], v[214:217], v[2:5]
	s_barrier
	s_add_i32 s63, s63, 2
	s_add_u32 s61, s61, 0x100
	s_addc_u32 s62, s62, 0
	s_cmpk_gt_u32 s63, 0x55
	s_mov_b64 s[24:25], s[36:37]
	s_cbranch_scc0 .LBB0_1127
	s_and_b64 vcc, exec, s[20:21]
	s_cbranch_vccz .LBB0_1130
	s_barrier
